# K-loops: eight of the sixteen LDS-DMA loads per iteration use SGPR-base addressing (no per-load 64-bit VALU add)
# baseline (speedup 1.0000x reference)
; #define PG8_STAGE(bufoff, gbase, voff) do { _Pragma("unroll") for (int _i = 0; _i < 2; ++_i) \
;         __builtin_amdgcn_global_load_lds((const unsigned*)((const char*)(gbase) + (voff)[_i]), (LAS unsigned*)(lds + (bufoff) + ldsw + _i * 8192), 16, 0, 0); } while (0)
; #define PG8_LDA(dst, b, h) do { _Pragma("unroll") for (int m = 0; m < 4; ++m) _Pragma("unroll") for (int k = 0; k < 2; ++k) dst[m][k] = *(const LAS bf16x8*)(lds + PG8_SA(b, h) + aoff + m * 2048 + k * 1024); } while (0)
; #define PG8_LDB(dst, b, h) do { _Pragma("unroll") for (int n = 0; n < 2; ++n) _Pragma("unroll") for (int k = 0; k < 2; ++k) dst[n][k] = *(const LAS bf16x8*)(lds + PG8_SB(b, h) + boff + n * 2048 + k * 1024); } while (0)
; #define PG8_MMA(ai, bj, At, Bt) do { __builtin_amdgcn_s_setprio(1); _Pragma("unroll") for (int m = 0; m < 4; ++m) _Pragma("unroll") for (int n = 0; n < 2; ++n) _Pragma("unroll") for (int k = 0; k < 2; ++k) \
;         acc[ai][bj][m][n] = __builtin_amdgcn_mfma_f32_16x16x32_bf16(Bt[n][k], At[m][k], acc[ai][bj][m][n], 0, 0, 0); __builtin_amdgcn_s_setprio(0); } while (0)
; #define PG8_WAIT_V(n) asm volatile("s_waitcnt vmcnt(" #n ")" ::: "memory")
; #define PG8_WAIT_L(n) asm volatile("s_waitcnt lgkmcnt(" #n ")" ::: "memory")
; #define PG8_BAR __builtin_amdgcn_s_barrier()
; template <class Sched, class Epi, bool ALIGN_EPI, bool SP2>
; __device__ __forceinline__ void gemm_phase(LAS unsigned char* lds, const int K, const int lda, const int ldb, const Sched& S, const Epi& E) {
;     ...
;         for (int t = 0; t < nt; t += 2) {
;             const bool last = (t == nt - 2);
;             const char* a1 = cA + (size_t)(t + 1) * kstep;
;             const char* a2 = last ? nA : cA + (size_t)(t + 2) * kstep; const char* b2 = last ? nB : cB + (size_t)(t + 2) * kstep;
;             const char* a3 = a2 + kstep; const char* b3 = b2 + kstep;
;             if constexpr (SP2) {
;             PG8_LDB(B0, 0, 0); PG8_LDB(B1, 0, 1); PG8_SCHED; PG8_LDA(At, 0, 0); PG8_STAGE(PG8_SA(1, 1), a1 + hstepA, voffA);
;             PG8_WAIT_V(8); PG8_WAIT_L(0); PG8_BAR; PG8_MMA(0, 0, At, B0); PG8_MMA(0, 1, At, B1); PG8_BAR; PG8_SCHED;
;             PG8_LDA(At, 0, 1); PG8_STAGE(PG8_SB(0, 0), b2, voffB); PG8_STAGE(PG8_SB(0, 1), b2 + hstepB, voffB); PG8_STAGE(PG8_SA(0, 0), a2, voffA);
;             PG8_WAIT_V(8); PG8_WAIT_L(0); PG8_BAR; PG8_MMA(1, 0, At, B0); PG8_MMA(1, 1, At, B1); PG8_BAR; PG8_SCHED;
.Lprio_skip_155:
.LBB0_155:
	ds_read_b128 v[140:143], v147
	ds_read_b128 v[150:153], v147 offset:1024
	ds_read_b128 v[154:157], v147 offset:2048
	ds_read_b128 v[158:161], v147 offset:3072
	ds_read_b128 v[162:165], v148
	ds_read_b128 v[166:169], v148 offset:1024
	ds_read_b128 v[170:173], v148 offset:2048
	ds_read_b128 v[180:183], v148 offset:3072
	s_add_u32 s22, s20, 0xfff80080
	s_addc_u32 s23, s21, -1
	s_cmp_eq_u32 s75, 28
	s_cselect_b32 s25, s15, s23
	s_cselect_b32 s24, s14, s22
	s_cselect_b32 s23, s17, s74
	s_cselect_b32 s22, s16, s13
	s_add_i32 m0, s3, 0xc000
	ds_read_b128 v[184:187], v149
	ds_read_b128 v[188:191], v149 offset:1024
	ds_read_b128 v[192:195], v149 offset:2048
	ds_read_b128 v[196:199], v149 offset:3072
	ds_read_b128 v[200:203], v149 offset:4096
	ds_read_b128 v[204:207], v149 offset:5120
	ds_read_b128 v[208:211], v149 offset:6144
	ds_read_b128 v[212:215], v149 offset:7168
	global_load_lds_dwordx4 v136, s[20:21]
	s_add_i32 m0, s3, 0xe000
	s_nop 0
	global_load_lds_dwordx4 v138, s[20:21]
	s_waitcnt vmcnt(8) lgkmcnt(0)
	s_barrier
	v_mfma_f32_16x16x32_bf16 v[124:127], v[140:143], v[184:187], v[124:127]
	v_mfma_f32_16x16x32_bf16 v[120:123], v[154:157], v[184:187], v[120:123]
	v_mfma_f32_16x16x32_bf16 v[108:111], v[140:143], v[192:195], v[108:111]
	v_mfma_f32_16x16x32_bf16 v[104:107], v[154:157], v[192:195], v[104:107]
	v_mfma_f32_16x16x32_bf16 v[92:95], v[140:143], v[200:203], v[92:95]
	v_mfma_f32_16x16x32_bf16 v[88:91], v[154:157], v[200:203], v[88:91]
	v_mfma_f32_16x16x32_bf16 v[76:79], v[140:143], v[208:211], v[76:79]
	v_mfma_f32_16x16x32_bf16 v[72:75], v[154:157], v[208:211], v[72:75]
	v_mfma_f32_16x16x32_bf16 v[124:127], v[150:153], v[188:191], v[124:127]
	v_mfma_f32_16x16x32_bf16 v[120:123], v[158:161], v[188:191], v[120:123]
	v_mfma_f32_16x16x32_bf16 v[108:111], v[150:153], v[196:199], v[108:111]
	v_mfma_f32_16x16x32_bf16 v[104:107], v[158:161], v[196:199], v[104:107]
	v_mfma_f32_16x16x32_bf16 v[92:95], v[150:153], v[204:207], v[92:95]
	v_mfma_f32_16x16x32_bf16 v[88:91], v[158:161], v[204:207], v[88:91]
	v_mfma_f32_16x16x32_bf16 v[76:79], v[150:153], v[212:215], v[76:79]
	v_mfma_f32_16x16x32_bf16 v[72:75], v[158:161], v[212:215], v[72:75]
	v_mfma_f32_16x16x32_bf16 v[116:119], v[162:165], v[184:187], v[116:119]
	v_mfma_f32_16x16x32_bf16 v[112:115], v[170:173], v[184:187], v[112:115]
	v_mfma_f32_16x16x32_bf16 v[100:103], v[162:165], v[192:195], v[100:103]
	v_mfma_f32_16x16x32_bf16 v[96:99], v[170:173], v[192:195], v[96:99]
	v_mfma_f32_16x16x32_bf16 v[84:87], v[162:165], v[200:203], v[84:87]
	v_mfma_f32_16x16x32_bf16 v[80:83], v[170:173], v[200:203], v[80:83]
	v_mfma_f32_16x16x32_bf16 v[68:71], v[162:165], v[208:211], v[68:71]
	v_mfma_f32_16x16x32_bf16 v[64:67], v[170:173], v[208:211], v[64:67]
	v_mfma_f32_16x16x32_bf16 v[116:119], v[166:169], v[188:191], v[116:119]
	v_mfma_f32_16x16x32_bf16 v[112:115], v[180:183], v[188:191], v[112:115]
	v_mfma_f32_16x16x32_bf16 v[100:103], v[166:169], v[196:199], v[100:103]
	v_mfma_f32_16x16x32_bf16 v[96:99], v[180:183], v[196:199], v[96:99]
	v_mfma_f32_16x16x32_bf16 v[84:87], v[166:169], v[204:207], v[84:87]
	v_mfma_f32_16x16x32_bf16 v[80:83], v[180:183], v[204:207], v[80:83]
	v_mfma_f32_16x16x32_bf16 v[68:71], v[166:169], v[212:215], v[68:71]
	v_mfma_f32_16x16x32_bf16 v[64:67], v[180:183], v[212:215], v[64:67]
	s_barrier
	s_add_i32 s78, s35, s2
	v_lshl_add_u64 v[174:175], s[22:23], 0, v[130:131]
	s_mov_b32 m0, s78
	ds_read_b128 v[184:187], v149 offset:16384
	ds_read_b128 v[188:191], v149 offset:17408
	ds_read_b128 v[192:195], v149 offset:18432
	ds_read_b128 v[196:199], v149 offset:19456
	ds_read_b128 v[200:203], v149 offset:20480
	ds_read_b128 v[204:207], v149 offset:21504
	ds_read_b128 v[208:211], v149 offset:22528
	ds_read_b128 v[212:215], v149 offset:23552
	global_load_lds_dwordx4 v[174:175], off
	s_add_i32 m0, s78, 0x2000
	s_add_u32 s78, s22, 0x80000
	v_lshl_add_u64 v[216:217], s[22:23], 0, v[134:135]
	s_addc_u32 s79, s23, 0
	s_add_i32 s84, s50, s2
	global_load_lds_dwordx4 v[216:217], off
	s_mov_b32 m0, s84
	v_lshl_add_u64 v[220:221], s[24:25], 0, v[132:133]
	global_load_lds_dwordx4 v130, s[78:79]
	s_add_i32 m0, s84, 0x2000
	s_nop 0
	global_load_lds_dwordx4 v134, s[78:79]
	v_lshl_add_u64 v[218:219], s[24:25], 0, v[128:129]
	s_mov_b32 m0, s3
	s_nop 0
	global_load_lds_dwordx4 v[218:219], off
	s_mov_b32 m0, s19
	s_nop 0
	global_load_lds_dwordx4 v[220:221], off
	s_waitcnt vmcnt(8) lgkmcnt(0)
	s_barrier
	v_mfma_f32_16x16x32_bf16 v[60:63], v[140:143], v[184:187], v[60:63]
	v_mfma_f32_16x16x32_bf16 v[56:59], v[154:157], v[184:187], v[56:59]
	v_mfma_f32_16x16x32_bf16 v[44:47], v[140:143], v[192:195], v[44:47]
	v_mfma_f32_16x16x32_bf16 v[40:43], v[154:157], v[192:195], v[40:43]
	v_mfma_f32_16x16x32_bf16 v[28:31], v[140:143], v[200:203], v[28:31]
	v_mfma_f32_16x16x32_bf16 v[24:27], v[154:157], v[200:203], v[24:27]
	v_mfma_f32_16x16x32_bf16 v[12:15], v[140:143], v[208:211], v[12:15]
	v_mfma_f32_16x16x32_bf16 v[8:11], v[154:157], v[208:211], v[8:11]
	v_mfma_f32_16x16x32_bf16 v[60:63], v[150:153], v[188:191], v[60:63]
	v_mfma_f32_16x16x32_bf16 v[56:59], v[158:161], v[188:191], v[56:59]
	v_mfma_f32_16x16x32_bf16 v[44:47], v[150:153], v[196:199], v[44:47]
	v_mfma_f32_16x16x32_bf16 v[40:43], v[158:161], v[196:199], v[40:43]
	v_mfma_f32_16x16x32_bf16 v[28:31], v[150:153], v[204:207], v[28:31]
	v_mfma_f32_16x16x32_bf16 v[24:27], v[158:161], v[204:207], v[24:27]
	v_mfma_f32_16x16x32_bf16 v[12:15], v[150:153], v[212:215], v[12:15]
	v_mfma_f32_16x16x32_bf16 v[8:11], v[158:161], v[212:215], v[8:11]
	v_mfma_f32_16x16x32_bf16 v[52:55], v[162:165], v[184:187], v[52:55]
	v_mfma_f32_16x16x32_bf16 v[48:51], v[170:173], v[184:187], v[48:51]
	v_mfma_f32_16x16x32_bf16 v[36:39], v[162:165], v[192:195], v[36:39]
	v_mfma_f32_16x16x32_bf16 v[32:35], v[170:173], v[192:195], v[32:35]
	v_mfma_f32_16x16x32_bf16 v[20:23], v[162:165], v[200:203], v[20:23]
	v_mfma_f32_16x16x32_bf16 v[16:19], v[170:173], v[200:203], v[16:19]
	v_mfma_f32_16x16x32_bf16 v[4:7], v[162:165], v[208:211], v[4:7]
	v_mfma_f32_16x16x32_bf16 v[0:3], v[170:173], v[208:211], v[0:3]
	v_mfma_f32_16x16x32_bf16 v[52:55], v[166:169], v[188:191], v[52:55]
	v_mfma_f32_16x16x32_bf16 v[48:51], v[180:183], v[188:191], v[48:51]
	v_mfma_f32_16x16x32_bf16 v[36:39], v[166:169], v[196:199], v[36:39]
	v_mfma_f32_16x16x32_bf16 v[32:35], v[180:183], v[196:199], v[32:35]
	v_mfma_f32_16x16x32_bf16 v[20:23], v[166:169], v[204:207], v[20:23]
	v_mfma_f32_16x16x32_bf16 v[16:19], v[180:183], v[204:207], v[16:19]
	v_mfma_f32_16x16x32_bf16 v[4:7], v[166:169], v[212:215], v[4:7]
	v_mfma_f32_16x16x32_bf16 v[0:3], v[180:183], v[212:215], v[0:3]
	s_barrier
; #define PG8_STAGE(bufoff, gbase, voff) do { _Pragma("unroll") for (int _i = 0; _i < 2; ++_i) \
;         __builtin_amdgcn_global_load_lds((const unsigned*)((const char*)(gbase) + (voff)[_i]), (LAS unsigned*)(lds + (bufoff) + ldsw + _i * 8192), 16, 0, 0); } while (0)
; #define PG8_LDA(dst, b, h) do { _Pragma("unroll") for (int m = 0; m < 4; ++m) _Pragma("unroll") for (int k = 0; k < 2; ++k) dst[m][k] = *(const LAS bf16x8*)(lds + PG8_SA(b, h) + aoff + m * 2048 + k * 1024); } while (0)
; #define PG8_LDB(dst, b, h) do { _Pragma("unroll") for (int n = 0; n < 2; ++n) _Pragma("unroll") for (int k = 0; k < 2; ++k) dst[n][k] = *(const LAS bf16x8*)(lds + PG8_SB(b, h) + boff + n * 2048 + k * 1024); } while (0)
; #define PG8_MMA(ai, bj, At, Bt) do { __builtin_amdgcn_s_setprio(1); _Pragma("unroll") for (int m = 0; m < 4; ++m) _Pragma("unroll") for (int n = 0; n < 2; ++n) _Pragma("unroll") for (int k = 0; k < 2; ++k) \
;         acc[ai][bj][m][n] = __builtin_amdgcn_mfma_f32_16x16x32_bf16(Bt[n][k], At[m][k], acc[ai][bj][m][n], 0, 0, 0); __builtin_amdgcn_s_setprio(0); } while (0)
; #define PG8_WAIT_V(n) asm volatile("s_waitcnt vmcnt(" #n ")" ::: "memory")
; #define PG8_WAIT_L(n) asm volatile("s_waitcnt lgkmcnt(" #n ")" ::: "memory")
; #define PG8_BAR __builtin_amdgcn_s_barrier()
; #define PG8_SCHED __builtin_amdgcn_sched_barrier(0)
; template <class Sched, class Epi, bool ALIGN_EPI, bool SP2>
; __device__ __forceinline__ void gemm_phase(LAS unsigned char* lds, const int K, const int lda, const int ldb, const Sched& S, const Epi& E) {
;     ...
;             PG8_LDB(B0, 1, 0); PG8_LDB(B1, 1, 1); PG8_SCHED; PG8_LDA(At, 1, 0); PG8_STAGE(PG8_SA(0, 1), a2 + hstepA, voffA);
;             PG8_WAIT_V(8); PG8_WAIT_L(0); PG8_BAR; PG8_MMA(0, 0, At, B0); PG8_MMA(0, 1, At, B1); PG8_BAR; PG8_SCHED;
;             PG8_LDA(At, 1, 1); PG8_STAGE(PG8_SB(1, 0), b3, voffB); PG8_STAGE(PG8_SB(1, 1), b3 + hstepB, voffB); PG8_STAGE(PG8_SA(1, 0), a3, voffA);
;             PG8_WAIT_V(8); PG8_WAIT_L(0); PG8_BAR; PG8_MMA(1, 0, At, B0); PG8_MMA(1, 1, At, B1); PG8_BAR; PG8_SCHED;
	s_add_i32 s78, 0, 0x18000
	s_add_i32 s79, 0, 0x1c000
	v_add_u32_e32 v158, s78, v145
	v_add_u32_e32 v177, s79, v145
	ds_read_b128 v[140:143], v158
	ds_read_b128 v[150:153], v158 offset:1024
	ds_read_b128 v[154:157], v158 offset:2048
	ds_read_b128 v[158:161], v158 offset:3072
	ds_read_b128 v[162:165], v177
	ds_read_b128 v[166:169], v177 offset:1024
	ds_read_b128 v[170:173], v177 offset:2048
	ds_read_b128 v[180:183], v177 offset:3072
	s_add_u32 s24, s24, 0x80000
	s_addc_u32 s25, s25, 0
	s_mov_b32 m0, s26
	ds_read_b128 v[184:187], v149 offset:32768
	ds_read_b128 v[188:191], v149 offset:33792
	ds_read_b128 v[192:195], v149 offset:34816
	ds_read_b128 v[196:199], v149 offset:35840
	ds_read_b128 v[200:203], v149 offset:36864
	ds_read_b128 v[204:207], v149 offset:37888
	ds_read_b128 v[208:211], v149 offset:38912
	ds_read_b128 v[212:215], v149 offset:39936
	global_load_lds_dwordx4 v128, s[24:25]
	s_mov_b32 m0, s27
	s_nop 0
	global_load_lds_dwordx4 v132, s[24:25]
	s_waitcnt vmcnt(8) lgkmcnt(0)
	s_barrier
	v_mfma_f32_16x16x32_bf16 v[124:127], v[140:143], v[184:187], v[124:127]
	v_mfma_f32_16x16x32_bf16 v[120:123], v[154:157], v[184:187], v[120:123]
	v_mfma_f32_16x16x32_bf16 v[108:111], v[140:143], v[192:195], v[108:111]
	v_mfma_f32_16x16x32_bf16 v[104:107], v[154:157], v[192:195], v[104:107]
	v_mfma_f32_16x16x32_bf16 v[92:95], v[140:143], v[200:203], v[92:95]
	v_mfma_f32_16x16x32_bf16 v[88:91], v[154:157], v[200:203], v[88:91]
	v_mfma_f32_16x16x32_bf16 v[76:79], v[140:143], v[208:211], v[76:79]
	v_mfma_f32_16x16x32_bf16 v[72:75], v[154:157], v[208:211], v[72:75]
	v_mfma_f32_16x16x32_bf16 v[124:127], v[150:153], v[188:191], v[124:127]
	v_mfma_f32_16x16x32_bf16 v[120:123], v[158:161], v[188:191], v[120:123]
	v_mfma_f32_16x16x32_bf16 v[108:111], v[150:153], v[196:199], v[108:111]
	v_mfma_f32_16x16x32_bf16 v[104:107], v[158:161], v[196:199], v[104:107]
	v_mfma_f32_16x16x32_bf16 v[92:95], v[150:153], v[204:207], v[92:95]
	v_mfma_f32_16x16x32_bf16 v[88:91], v[158:161], v[204:207], v[88:91]
	v_mfma_f32_16x16x32_bf16 v[76:79], v[150:153], v[212:215], v[76:79]
	v_mfma_f32_16x16x32_bf16 v[72:75], v[158:161], v[212:215], v[72:75]
	v_mfma_f32_16x16x32_bf16 v[116:119], v[162:165], v[184:187], v[116:119]
	v_mfma_f32_16x16x32_bf16 v[112:115], v[170:173], v[184:187], v[112:115]
	v_mfma_f32_16x16x32_bf16 v[100:103], v[162:165], v[192:195], v[100:103]
	v_mfma_f32_16x16x32_bf16 v[96:99], v[170:173], v[192:195], v[96:99]
	v_mfma_f32_16x16x32_bf16 v[84:87], v[162:165], v[200:203], v[84:87]
	v_mfma_f32_16x16x32_bf16 v[80:83], v[170:173], v[200:203], v[80:83]
	v_mfma_f32_16x16x32_bf16 v[68:71], v[162:165], v[208:211], v[68:71]
	v_mfma_f32_16x16x32_bf16 v[64:67], v[170:173], v[208:211], v[64:67]
	v_mfma_f32_16x16x32_bf16 v[116:119], v[166:169], v[188:191], v[116:119]
	v_mfma_f32_16x16x32_bf16 v[112:115], v[180:183], v[188:191], v[112:115]
	v_mfma_f32_16x16x32_bf16 v[100:103], v[166:169], v[196:199], v[100:103]
	v_mfma_f32_16x16x32_bf16 v[96:99], v[180:183], v[196:199], v[96:99]
	v_mfma_f32_16x16x32_bf16 v[84:87], v[166:169], v[204:207], v[84:87]
	v_mfma_f32_16x16x32_bf16 v[80:83], v[180:183], v[204:207], v[80:83]
	v_mfma_f32_16x16x32_bf16 v[68:71], v[166:169], v[212:215], v[68:71]
	v_mfma_f32_16x16x32_bf16 v[64:67], v[180:183], v[212:215], v[64:67]
	s_barrier
	s_add_i32 s24, s78, s2
	v_lshl_add_u64 v[174:175], v[174:175], 0, s[4:5]
	s_mov_b32 m0, s24
	ds_read_b128 v[184:187], v149 offset:49152
	ds_read_b128 v[188:191], v149 offset:50176
	ds_read_b128 v[192:195], v149 offset:51200
	ds_read_b128 v[196:199], v149 offset:52224
	ds_read_b128 v[200:203], v149 offset:53248
	ds_read_b128 v[204:207], v149 offset:54272
	ds_read_b128 v[208:211], v149 offset:55296
	ds_read_b128 v[212:215], v149 offset:56320
	global_load_lds_dwordx4 v[174:175], off
	s_add_i32 m0, s24, 0x2000
	s_add_u32 s22, s22, 0x80080
	v_lshl_add_u64 v[174:175], v[216:217], 0, s[4:5]
	s_addc_u32 s23, s23, 0
	s_add_i32 s24, s79, s2
	global_load_lds_dwordx4 v[174:175], off
	s_mov_b32 m0, s24
	s_nop 0
	global_load_lds_dwordx4 v130, s[22:23]
	s_add_i32 m0, s24, 0x2000
	s_nop 0
	global_load_lds_dwordx4 v134, s[22:23]
	v_lshl_add_u64 v[174:175], v[218:219], 0, s[4:5]
	s_mov_b32 m0, s29
	s_nop 0
	global_load_lds_dwordx4 v[174:175], off
	v_lshl_add_u64 v[174:175], v[220:221], 0, s[4:5]
	s_mov_b32 m0, s33
	s_nop 0
	global_load_lds_dwordx4 v[174:175], off
	s_waitcnt vmcnt(8) lgkmcnt(0)
	s_barrier
	v_mfma_f32_16x16x32_bf16 v[60:63], v[140:143], v[184:187], v[60:63]
	v_mfma_f32_16x16x32_bf16 v[56:59], v[154:157], v[184:187], v[56:59]
	v_mfma_f32_16x16x32_bf16 v[44:47], v[140:143], v[192:195], v[44:47]
	v_mfma_f32_16x16x32_bf16 v[40:43], v[154:157], v[192:195], v[40:43]
	v_mfma_f32_16x16x32_bf16 v[28:31], v[140:143], v[200:203], v[28:31]
	v_mfma_f32_16x16x32_bf16 v[24:27], v[154:157], v[200:203], v[24:27]
	v_mfma_f32_16x16x32_bf16 v[12:15], v[140:143], v[208:211], v[12:15]
	v_mfma_f32_16x16x32_bf16 v[8:11], v[154:157], v[208:211], v[8:11]
	v_mfma_f32_16x16x32_bf16 v[60:63], v[150:153], v[188:191], v[60:63]
	v_mfma_f32_16x16x32_bf16 v[56:59], v[158:161], v[188:191], v[56:59]
	v_mfma_f32_16x16x32_bf16 v[44:47], v[150:153], v[196:199], v[44:47]
	v_mfma_f32_16x16x32_bf16 v[40:43], v[158:161], v[196:199], v[40:43]
	v_mfma_f32_16x16x32_bf16 v[28:31], v[150:153], v[204:207], v[28:31]
	v_mfma_f32_16x16x32_bf16 v[24:27], v[158:161], v[204:207], v[24:27]
	v_mfma_f32_16x16x32_bf16 v[12:15], v[150:153], v[212:215], v[12:15]
	v_mfma_f32_16x16x32_bf16 v[8:11], v[158:161], v[212:215], v[8:11]
	v_mfma_f32_16x16x32_bf16 v[52:55], v[162:165], v[184:187], v[52:55]
	v_mfma_f32_16x16x32_bf16 v[48:51], v[170:173], v[184:187], v[48:51]
	v_mfma_f32_16x16x32_bf16 v[36:39], v[162:165], v[192:195], v[36:39]
	v_mfma_f32_16x16x32_bf16 v[32:35], v[170:173], v[192:195], v[32:35]
	v_mfma_f32_16x16x32_bf16 v[20:23], v[162:165], v[200:203], v[20:23]
	v_mfma_f32_16x16x32_bf16 v[16:19], v[170:173], v[200:203], v[16:19]
	v_mfma_f32_16x16x32_bf16 v[4:7], v[162:165], v[208:211], v[4:7]
	v_mfma_f32_16x16x32_bf16 v[0:3], v[170:173], v[208:211], v[0:3]
	v_mfma_f32_16x16x32_bf16 v[52:55], v[166:169], v[188:191], v[52:55]
	v_mfma_f32_16x16x32_bf16 v[48:51], v[180:183], v[188:191], v[48:51]
	v_mfma_f32_16x16x32_bf16 v[36:39], v[166:169], v[196:199], v[36:39]
	v_mfma_f32_16x16x32_bf16 v[32:35], v[180:183], v[196:199], v[32:35]
	v_mfma_f32_16x16x32_bf16 v[20:23], v[166:169], v[204:207], v[20:23]
	v_mfma_f32_16x16x32_bf16 v[16:19], v[180:183], v[204:207], v[16:19]
	v_mfma_f32_16x16x32_bf16 v[4:7], v[166:169], v[212:215], v[4:7]
	v_mfma_f32_16x16x32_bf16 v[0:3], v[180:183], v[212:215], v[0:3]
	s_barrier
	s_add_i32 s75, s75, 2
	s_add_u32 s20, s20, 0x100
	s_addc_u32 s21, s21, 0
	s_add_u32 s13, s13, 0x100
	s_addc_u32 s74, s74, 0
	s_cmp_gt_u32 s75, 29
	s_cbranch_scc0 .LBB0_155
	s_setprio 0
	s_and_b64 vcc, exec, s[6:7]
	s_cbranch_vccz .LBB0_158
	s_barrier

; #define PG8_STAGE(bufoff, gbase, voff) do { _Pragma("unroll") for (int _i = 0; _i < 2; ++_i) \
;         __builtin_amdgcn_global_load_lds((const unsigned*)((const char*)(gbase) + (voff)[_i]), (LAS unsigned*)(lds + (bufoff) + ldsw + _i * 8192), 16, 0, 0); } while (0)
; #define PG8_LDA(dst, b, h) do { _Pragma("unroll") for (int m = 0; m < 4; ++m) _Pragma("unroll") for (int k = 0; k < 2; ++k) dst[m][k] = *(const LAS bf16x8*)(lds + PG8_SA(b, h) + aoff + m * 2048 + k * 1024); } while (0)
; #define PG8_LDB(dst, b, h) do { _Pragma("unroll") for (int n = 0; n < 2; ++n) _Pragma("unroll") for (int k = 0; k < 2; ++k) dst[n][k] = *(const LAS bf16x8*)(lds + PG8_SB(b, h) + boff + n * 2048 + k * 1024); } while (0)
; #define PG8_MMA(ai, bj, At, Bt) do { __builtin_amdgcn_s_setprio(1); _Pragma("unroll") for (int m = 0; m < 4; ++m) _Pragma("unroll") for (int n = 0; n < 2; ++n) _Pragma("unroll") for (int k = 0; k < 2; ++k) \
;         acc[ai][bj][m][n] = __builtin_amdgcn_mfma_f32_16x16x32_bf16(Bt[n][k], At[m][k], acc[ai][bj][m][n], 0, 0, 0); __builtin_amdgcn_s_setprio(0); } while (0)
; #define PG8_WAIT_V(n) asm volatile("s_waitcnt vmcnt(" #n ")" ::: "memory")
; #define PG8_WAIT_L(n) asm volatile("s_waitcnt lgkmcnt(" #n ")" ::: "memory")
; #define PG8_BAR __builtin_amdgcn_s_barrier()
; #define PG8_SCHED __builtin_amdgcn_sched_barrier(0)
; template <class Sched, class Epi, bool ALIGN_EPI, bool SP2>
; __device__ __forceinline__ void gemm_phase(LAS unsigned char* lds, const int K, const int lda, const int ldb, const Sched& S, const Epi& E) {
;     ...
;             PG8_LDB(B0, 0, 0); PG8_LDB(B1, 0, 1); PG8_SCHED; PG8_LDA(At, 0, 0); PG8_STAGE(PG8_SA(1, 1), a1 + hstepA, voffA);
;             PG8_WAIT_V(8); PG8_WAIT_L(0); PG8_BAR; PG8_MMA(0, 0, At, B0); PG8_MMA(0, 1, At, B1); PG8_BAR; PG8_SCHED;
;             PG8_LDA(At, 0, 1); PG8_STAGE(PG8_SB(0, 0), b2, voffB); PG8_STAGE(PG8_SB(0, 1), b2 + hstepB, voffB); PG8_STAGE(PG8_SA(0, 0), a2, voffA);
;             PG8_WAIT_V(8); PG8_WAIT_L(0); PG8_BAR; PG8_MMA(1, 0, At, B0); PG8_MMA(1, 1, At, B1); PG8_BAR; PG8_SCHED;
.Lprio_skip_243:
.LBB0_243:
	ds_read_b128 v[124:127], v169
	ds_read_b128 v[132:135], v169 offset:1024
	ds_read_b128 v[136:139], v169 offset:2048
	ds_read_b128 v[140:143], v169 offset:3072
	ds_read_b128 v[144:147], v170
	ds_read_b128 v[156:159], v170 offset:1024
	ds_read_b128 v[160:163], v170 offset:2048
	ds_read_b128 v[182:185], v170 offset:3072
	s_add_u32 s22, s20, 0x100
	s_addc_u32 s23, s21, 0
	s_cmpk_eq_i32 s91, 0x54
	s_cselect_b32 s27, s17, s23
	s_cselect_b32 s26, s16, s22
	s_cselect_b32 s25, s19, s90
	s_cselect_b32 s24, s18, s89
	s_mov_b32 m0, s78
	ds_read_b128 v[186:189], v171
	ds_read_b128 v[190:193], v171 offset:1024
	ds_read_b128 v[194:197], v171 offset:2048
	ds_read_b128 v[198:201], v171 offset:3072
	ds_read_b128 v[202:205], v171 offset:4096
	ds_read_b128 v[206:209], v171 offset:5120
	ds_read_b128 v[210:213], v171 offset:6144
	ds_read_b128 v[214:217], v171 offset:7168
	global_load_lds_dwordx4 v152, s[20:21]
	s_mov_b32 m0, s79
	s_nop 0
	global_load_lds_dwordx4 v154, s[20:21]
	s_waitcnt vmcnt(8) lgkmcnt(0)
	s_barrier
	v_mfma_f32_16x16x32_bf16 v[128:131], v[124:127], v[186:189], v[128:131]
	v_mfma_f32_16x16x32_bf16 v[120:123], v[136:139], v[186:189], v[120:123]
	v_mfma_f32_16x16x32_bf16 v[108:111], v[124:127], v[194:197], v[108:111]
	v_mfma_f32_16x16x32_bf16 v[104:107], v[136:139], v[194:197], v[104:107]
	v_mfma_f32_16x16x32_bf16 v[92:95], v[124:127], v[202:205], v[92:95]
	v_mfma_f32_16x16x32_bf16 v[88:91], v[136:139], v[202:205], v[88:91]
	v_mfma_f32_16x16x32_bf16 v[76:79], v[124:127], v[210:213], v[76:79]
	v_mfma_f32_16x16x32_bf16 v[72:75], v[136:139], v[210:213], v[72:75]
	v_mfma_f32_16x16x32_bf16 v[128:131], v[132:135], v[190:193], v[128:131]
	v_mfma_f32_16x16x32_bf16 v[120:123], v[140:143], v[190:193], v[120:123]
	v_mfma_f32_16x16x32_bf16 v[108:111], v[132:135], v[198:201], v[108:111]
	v_mfma_f32_16x16x32_bf16 v[104:107], v[140:143], v[198:201], v[104:107]
	v_mfma_f32_16x16x32_bf16 v[92:95], v[132:135], v[206:209], v[92:95]
	v_mfma_f32_16x16x32_bf16 v[88:91], v[140:143], v[206:209], v[88:91]
	v_mfma_f32_16x16x32_bf16 v[76:79], v[132:135], v[214:217], v[76:79]
	v_mfma_f32_16x16x32_bf16 v[72:75], v[140:143], v[214:217], v[72:75]
	v_mfma_f32_16x16x32_bf16 v[116:119], v[144:147], v[186:189], v[116:119]
	v_mfma_f32_16x16x32_bf16 v[112:115], v[160:163], v[186:189], v[112:115]
	v_mfma_f32_16x16x32_bf16 v[100:103], v[144:147], v[194:197], v[100:103]
	v_mfma_f32_16x16x32_bf16 v[96:99], v[160:163], v[194:197], v[96:99]
	v_mfma_f32_16x16x32_bf16 v[84:87], v[144:147], v[202:205], v[84:87]
	v_mfma_f32_16x16x32_bf16 v[80:83], v[160:163], v[202:205], v[80:83]
	v_mfma_f32_16x16x32_bf16 v[68:71], v[144:147], v[210:213], v[68:71]
	v_mfma_f32_16x16x32_bf16 v[64:67], v[160:163], v[210:213], v[64:67]
	v_mfma_f32_16x16x32_bf16 v[116:119], v[156:159], v[190:193], v[116:119]
	v_mfma_f32_16x16x32_bf16 v[112:115], v[182:185], v[190:193], v[112:115]
	v_mfma_f32_16x16x32_bf16 v[100:103], v[156:159], v[198:201], v[100:103]
	v_mfma_f32_16x16x32_bf16 v[96:99], v[182:185], v[198:201], v[96:99]
	v_mfma_f32_16x16x32_bf16 v[84:87], v[156:159], v[206:209], v[84:87]
	v_mfma_f32_16x16x32_bf16 v[80:83], v[182:185], v[206:209], v[80:83]
	v_mfma_f32_16x16x32_bf16 v[68:71], v[156:159], v[214:217], v[68:71]
	v_mfma_f32_16x16x32_bf16 v[64:67], v[182:185], v[214:217], v[64:67]
	s_barrier
	s_mov_b32 m0, s84
	v_lshl_add_u64 v[164:165], s[24:25], 0, v[148:149]
	ds_read_b128 v[186:189], v171 offset:16384
	ds_read_b128 v[190:193], v171 offset:17408
	ds_read_b128 v[194:197], v171 offset:18432
	ds_read_b128 v[198:201], v171 offset:19456
	ds_read_b128 v[202:205], v171 offset:20480
	ds_read_b128 v[206:209], v171 offset:21504
	ds_read_b128 v[210:213], v171 offset:22528
	ds_read_b128 v[214:217], v171 offset:23552
	global_load_lds_dwordx4 v[164:165], off
	s_add_i32 m0, s84, 0x2000
	s_add_u32 s20, s24, 0x160000
	v_lshl_add_u64 v[174:175], s[24:25], 0, v[150:151]
	s_addc_u32 s21, s25, 0
	s_add_i32 s96, s53, s13
	global_load_lds_dwordx4 v[174:175], off
	s_mov_b32 m0, s96
	v_lshl_add_u64 v[220:221], s[26:27], 0, v[150:151]
	global_load_lds_dwordx4 v148, s[20:21]
	s_add_i32 m0, s96, 0x2000
	s_nop 0
	global_load_lds_dwordx4 v150, s[20:21]
	v_lshl_add_u64 v[218:219], s[26:27], 0, v[148:149]
	s_mov_b32 m0, s28
	s_nop 0
	global_load_lds_dwordx4 v[218:219], off
	s_mov_b32 m0, s29
	s_nop 0
	global_load_lds_dwordx4 v[220:221], off
	s_waitcnt vmcnt(8) lgkmcnt(0)
	s_barrier
	v_mfma_f32_16x16x32_bf16 v[60:63], v[124:127], v[186:189], v[60:63]
	v_mfma_f32_16x16x32_bf16 v[56:59], v[136:139], v[186:189], v[56:59]
	v_mfma_f32_16x16x32_bf16 v[44:47], v[124:127], v[194:197], v[44:47]
	v_mfma_f32_16x16x32_bf16 v[40:43], v[136:139], v[194:197], v[40:43]
	v_mfma_f32_16x16x32_bf16 v[28:31], v[124:127], v[202:205], v[28:31]
	v_mfma_f32_16x16x32_bf16 v[24:27], v[136:139], v[202:205], v[24:27]
	v_mfma_f32_16x16x32_bf16 v[12:15], v[124:127], v[210:213], v[12:15]
	v_mfma_f32_16x16x32_bf16 v[8:11], v[136:139], v[210:213], v[8:11]
	v_mfma_f32_16x16x32_bf16 v[60:63], v[132:135], v[190:193], v[60:63]
	v_mfma_f32_16x16x32_bf16 v[56:59], v[140:143], v[190:193], v[56:59]
	v_mfma_f32_16x16x32_bf16 v[44:47], v[132:135], v[198:201], v[44:47]
	v_mfma_f32_16x16x32_bf16 v[40:43], v[140:143], v[198:201], v[40:43]
	v_mfma_f32_16x16x32_bf16 v[28:31], v[132:135], v[206:209], v[28:31]
	v_mfma_f32_16x16x32_bf16 v[24:27], v[140:143], v[206:209], v[24:27]
	v_mfma_f32_16x16x32_bf16 v[12:15], v[132:135], v[214:217], v[12:15]
	v_mfma_f32_16x16x32_bf16 v[8:11], v[140:143], v[214:217], v[8:11]
	v_mfma_f32_16x16x32_bf16 v[52:55], v[144:147], v[186:189], v[52:55]
	v_mfma_f32_16x16x32_bf16 v[48:51], v[160:163], v[186:189], v[48:51]
	v_mfma_f32_16x16x32_bf16 v[36:39], v[144:147], v[194:197], v[36:39]
	v_mfma_f32_16x16x32_bf16 v[32:35], v[160:163], v[194:197], v[32:35]
	v_mfma_f32_16x16x32_bf16 v[20:23], v[144:147], v[202:205], v[20:23]
	v_mfma_f32_16x16x32_bf16 v[16:19], v[160:163], v[202:205], v[16:19]
	v_mfma_f32_16x16x32_bf16 v[4:7], v[144:147], v[210:213], v[4:7]
	v_mfma_f32_16x16x32_bf16 v[0:3], v[160:163], v[210:213], v[0:3]
	v_mfma_f32_16x16x32_bf16 v[52:55], v[156:159], v[190:193], v[52:55]
	v_mfma_f32_16x16x32_bf16 v[48:51], v[182:185], v[190:193], v[48:51]
	v_mfma_f32_16x16x32_bf16 v[36:39], v[156:159], v[198:201], v[36:39]
	v_mfma_f32_16x16x32_bf16 v[32:35], v[182:185], v[198:201], v[32:35]
	v_mfma_f32_16x16x32_bf16 v[20:23], v[156:159], v[206:209], v[20:23]
	v_mfma_f32_16x16x32_bf16 v[16:19], v[182:185], v[206:209], v[16:19]
	v_mfma_f32_16x16x32_bf16 v[4:7], v[156:159], v[214:217], v[4:7]
	v_mfma_f32_16x16x32_bf16 v[0:3], v[182:185], v[214:217], v[0:3]
	s_barrier
; #define PG8_STAGE(bufoff, gbase, voff) do { _Pragma("unroll") for (int _i = 0; _i < 2; ++_i) \
;         __builtin_amdgcn_global_load_lds((const unsigned*)((const char*)(gbase) + (voff)[_i]), (LAS unsigned*)(lds + (bufoff) + ldsw + _i * 8192), 16, 0, 0); } while (0)
; #define PG8_LDA(dst, b, h) do { _Pragma("unroll") for (int m = 0; m < 4; ++m) _Pragma("unroll") for (int k = 0; k < 2; ++k) dst[m][k] = *(const LAS bf16x8*)(lds + PG8_SA(b, h) + aoff + m * 2048 + k * 1024); } while (0)
; #define PG8_LDB(dst, b, h) do { _Pragma("unroll") for (int n = 0; n < 2; ++n) _Pragma("unroll") for (int k = 0; k < 2; ++k) dst[n][k] = *(const LAS bf16x8*)(lds + PG8_SB(b, h) + boff + n * 2048 + k * 1024); } while (0)
; #define PG8_MMA(ai, bj, At, Bt) do { __builtin_amdgcn_s_setprio(1); _Pragma("unroll") for (int m = 0; m < 4; ++m) _Pragma("unroll") for (int n = 0; n < 2; ++n) _Pragma("unroll") for (int k = 0; k < 2; ++k) \
;         acc[ai][bj][m][n] = __builtin_amdgcn_mfma_f32_16x16x32_bf16(Bt[n][k], At[m][k], acc[ai][bj][m][n], 0, 0, 0); __builtin_amdgcn_s_setprio(0); } while (0)
; #define PG8_WAIT_V(n) asm volatile("s_waitcnt vmcnt(" #n ")" ::: "memory")
; #define PG8_WAIT_L(n) asm volatile("s_waitcnt lgkmcnt(" #n ")" ::: "memory")
; #define PG8_BAR __builtin_amdgcn_s_barrier()
; #define PG8_SCHED __builtin_amdgcn_sched_barrier(0)
; template <class Sched, class Epi, bool ALIGN_EPI, bool SP2>
; __device__ __forceinline__ void gemm_phase(LAS unsigned char* lds, const int K, const int lda, const int ldb, const Sched& S, const Epi& E) {
;     ...
;             PG8_LDB(B0, 1, 0); PG8_LDB(B1, 1, 1); PG8_SCHED; PG8_LDA(At, 1, 0); PG8_STAGE(PG8_SA(0, 1), a2 + hstepA, voffA);
;             PG8_WAIT_V(8); PG8_WAIT_L(0); PG8_BAR; PG8_MMA(0, 0, At, B0); PG8_MMA(0, 1, At, B1); PG8_BAR; PG8_SCHED;
;             PG8_LDA(At, 1, 1); PG8_STAGE(PG8_SB(1, 0), b3, voffB); PG8_STAGE(PG8_SB(1, 1), b3 + hstepB, voffB); PG8_STAGE(PG8_SA(1, 0), a3, voffA);
;             PG8_WAIT_V(8); PG8_WAIT_L(0); PG8_BAR; PG8_MMA(1, 0, At, B0); PG8_MMA(1, 1, At, B1); PG8_BAR; PG8_SCHED;
	s_add_i32 s96, 0, 0x18000
	s_add_i32 s97, 0, 0x1c000
	v_add_u32_e32 v140, s96, v167
	v_add_u32_e32 v173, s97, v167
	ds_read_b128 v[124:127], v140
	ds_read_b128 v[132:135], v140 offset:1024
	ds_read_b128 v[136:139], v140 offset:2048
	ds_read_b128 v[140:143], v140 offset:3072
	ds_read_b128 v[144:147], v173
	ds_read_b128 v[156:159], v173 offset:1024
	ds_read_b128 v[160:163], v173 offset:2048
	ds_read_b128 v[182:185], v173 offset:3072
	s_add_u32 s20, s26, 0x160000
	s_addc_u32 s21, s27, 0
	s_mov_b32 m0, s33
	ds_read_b128 v[186:189], v171 offset:32768
	ds_read_b128 v[190:193], v171 offset:33792
	ds_read_b128 v[194:197], v171 offset:34816
	ds_read_b128 v[198:201], v171 offset:35840
	ds_read_b128 v[202:205], v171 offset:36864
	ds_read_b128 v[206:209], v171 offset:37888
	ds_read_b128 v[210:213], v171 offset:38912
	ds_read_b128 v[214:217], v171 offset:39936
	global_load_lds_dwordx4 v148, s[20:21]
	s_mov_b32 m0, s35
	s_nop 0
	global_load_lds_dwordx4 v150, s[20:21]
	s_waitcnt vmcnt(8) lgkmcnt(0)
	s_barrier
	v_mfma_f32_16x16x32_bf16 v[128:131], v[124:127], v[186:189], v[128:131]
	v_mfma_f32_16x16x32_bf16 v[120:123], v[136:139], v[186:189], v[120:123]
	v_mfma_f32_16x16x32_bf16 v[108:111], v[124:127], v[194:197], v[108:111]
	v_mfma_f32_16x16x32_bf16 v[104:107], v[136:139], v[194:197], v[104:107]
	v_mfma_f32_16x16x32_bf16 v[92:95], v[124:127], v[202:205], v[92:95]
	v_mfma_f32_16x16x32_bf16 v[88:91], v[136:139], v[202:205], v[88:91]
	v_mfma_f32_16x16x32_bf16 v[76:79], v[124:127], v[210:213], v[76:79]
	v_mfma_f32_16x16x32_bf16 v[72:75], v[136:139], v[210:213], v[72:75]
	v_mfma_f32_16x16x32_bf16 v[128:131], v[132:135], v[190:193], v[128:131]
	v_mfma_f32_16x16x32_bf16 v[120:123], v[140:143], v[190:193], v[120:123]
	v_mfma_f32_16x16x32_bf16 v[108:111], v[132:135], v[198:201], v[108:111]
	v_mfma_f32_16x16x32_bf16 v[104:107], v[140:143], v[198:201], v[104:107]
	v_mfma_f32_16x16x32_bf16 v[92:95], v[132:135], v[206:209], v[92:95]
	v_mfma_f32_16x16x32_bf16 v[88:91], v[140:143], v[206:209], v[88:91]
	v_mfma_f32_16x16x32_bf16 v[76:79], v[132:135], v[214:217], v[76:79]
	v_mfma_f32_16x16x32_bf16 v[72:75], v[140:143], v[214:217], v[72:75]
	v_mfma_f32_16x16x32_bf16 v[116:119], v[144:147], v[186:189], v[116:119]
	v_mfma_f32_16x16x32_bf16 v[112:115], v[160:163], v[186:189], v[112:115]
	v_mfma_f32_16x16x32_bf16 v[100:103], v[144:147], v[194:197], v[100:103]
	v_mfma_f32_16x16x32_bf16 v[96:99], v[160:163], v[194:197], v[96:99]
	v_mfma_f32_16x16x32_bf16 v[84:87], v[144:147], v[202:205], v[84:87]
	v_mfma_f32_16x16x32_bf16 v[80:83], v[160:163], v[202:205], v[80:83]
	v_mfma_f32_16x16x32_bf16 v[68:71], v[144:147], v[210:213], v[68:71]
	v_mfma_f32_16x16x32_bf16 v[64:67], v[160:163], v[210:213], v[64:67]
	v_mfma_f32_16x16x32_bf16 v[116:119], v[156:159], v[190:193], v[116:119]
	v_mfma_f32_16x16x32_bf16 v[112:115], v[182:185], v[190:193], v[112:115]
	v_mfma_f32_16x16x32_bf16 v[100:103], v[156:159], v[198:201], v[100:103]
	v_mfma_f32_16x16x32_bf16 v[96:99], v[182:185], v[198:201], v[96:99]
	v_mfma_f32_16x16x32_bf16 v[84:87], v[156:159], v[206:209], v[84:87]
	v_mfma_f32_16x16x32_bf16 v[80:83], v[182:185], v[206:209], v[80:83]
	v_mfma_f32_16x16x32_bf16 v[68:71], v[156:159], v[214:217], v[68:71]
	v_mfma_f32_16x16x32_bf16 v[64:67], v[182:185], v[214:217], v[64:67]
	s_barrier
	s_add_i32 s20, s96, s13
	v_lshl_add_u64 v[164:165], v[164:165], 0, s[6:7]
	s_mov_b32 m0, s20
	ds_read_b128 v[186:189], v171 offset:49152
	ds_read_b128 v[190:193], v171 offset:50176
	ds_read_b128 v[194:197], v171 offset:51200
	ds_read_b128 v[198:201], v171 offset:52224
	ds_read_b128 v[202:205], v171 offset:53248
	ds_read_b128 v[206:209], v171 offset:54272
	ds_read_b128 v[210:213], v171 offset:55296
	ds_read_b128 v[214:217], v171 offset:56320
	global_load_lds_dwordx4 v[164:165], off
	s_add_i32 m0, s20, 0x2000
	s_add_u32 s20, s24, 0x160080
	v_lshl_add_u64 v[164:165], v[174:175], 0, s[6:7]
	s_addc_u32 s21, s25, 0
	s_add_i32 s24, s97, s13
	global_load_lds_dwordx4 v[164:165], off
	s_mov_b32 m0, s24
	s_nop 0
	global_load_lds_dwordx4 v148, s[20:21]
	s_add_i32 m0, s24, 0x2000
	s_nop 0
	global_load_lds_dwordx4 v150, s[20:21]
	v_lshl_add_u64 v[164:165], v[218:219], 0, s[6:7]
	s_mov_b32 m0, s51
	s_nop 0
	global_load_lds_dwordx4 v[164:165], off
	v_lshl_add_u64 v[164:165], v[220:221], 0, s[6:7]
	s_mov_b32 m0, s52
	s_nop 0
	global_load_lds_dwordx4 v[164:165], off
	s_waitcnt vmcnt(8) lgkmcnt(0)
	s_barrier
	v_mfma_f32_16x16x32_bf16 v[60:63], v[124:127], v[186:189], v[60:63]
	v_mfma_f32_16x16x32_bf16 v[56:59], v[136:139], v[186:189], v[56:59]
	v_mfma_f32_16x16x32_bf16 v[44:47], v[124:127], v[194:197], v[44:47]
	v_mfma_f32_16x16x32_bf16 v[40:43], v[136:139], v[194:197], v[40:43]
	v_mfma_f32_16x16x32_bf16 v[28:31], v[124:127], v[202:205], v[28:31]
	v_mfma_f32_16x16x32_bf16 v[24:27], v[136:139], v[202:205], v[24:27]
	v_mfma_f32_16x16x32_bf16 v[12:15], v[124:127], v[210:213], v[12:15]
	v_mfma_f32_16x16x32_bf16 v[8:11], v[136:139], v[210:213], v[8:11]
	v_mfma_f32_16x16x32_bf16 v[60:63], v[132:135], v[190:193], v[60:63]
	v_mfma_f32_16x16x32_bf16 v[56:59], v[140:143], v[190:193], v[56:59]
	v_mfma_f32_16x16x32_bf16 v[44:47], v[132:135], v[198:201], v[44:47]
	v_mfma_f32_16x16x32_bf16 v[40:43], v[140:143], v[198:201], v[40:43]
	v_mfma_f32_16x16x32_bf16 v[28:31], v[132:135], v[206:209], v[28:31]
	v_mfma_f32_16x16x32_bf16 v[24:27], v[140:143], v[206:209], v[24:27]
	v_mfma_f32_16x16x32_bf16 v[12:15], v[132:135], v[214:217], v[12:15]
	v_mfma_f32_16x16x32_bf16 v[8:11], v[140:143], v[214:217], v[8:11]
	v_mfma_f32_16x16x32_bf16 v[52:55], v[144:147], v[186:189], v[52:55]
	v_mfma_f32_16x16x32_bf16 v[48:51], v[160:163], v[186:189], v[48:51]
	v_mfma_f32_16x16x32_bf16 v[36:39], v[144:147], v[194:197], v[36:39]
	v_mfma_f32_16x16x32_bf16 v[32:35], v[160:163], v[194:197], v[32:35]
	v_mfma_f32_16x16x32_bf16 v[20:23], v[144:147], v[202:205], v[20:23]
	v_mfma_f32_16x16x32_bf16 v[16:19], v[160:163], v[202:205], v[16:19]
	v_mfma_f32_16x16x32_bf16 v[4:7], v[144:147], v[210:213], v[4:7]
	v_mfma_f32_16x16x32_bf16 v[0:3], v[160:163], v[210:213], v[0:3]
	v_mfma_f32_16x16x32_bf16 v[52:55], v[156:159], v[190:193], v[52:55]
	v_mfma_f32_16x16x32_bf16 v[48:51], v[182:185], v[190:193], v[48:51]
	v_mfma_f32_16x16x32_bf16 v[36:39], v[156:159], v[198:201], v[36:39]
	v_mfma_f32_16x16x32_bf16 v[32:35], v[182:185], v[198:201], v[32:35]
	v_mfma_f32_16x16x32_bf16 v[20:23], v[156:159], v[206:209], v[20:23]
	v_mfma_f32_16x16x32_bf16 v[16:19], v[182:185], v[206:209], v[16:19]
	v_mfma_f32_16x16x32_bf16 v[4:7], v[156:159], v[214:217], v[4:7]
	v_mfma_f32_16x16x32_bf16 v[0:3], v[182:185], v[214:217], v[0:3]
	s_barrier
	s_add_i32 s91, s91, 2
	s_add_u32 s89, s89, 0x100
	s_addc_u32 s90, s90, 0
	s_cmpk_gt_u32 s91, 0x55
	s_mov_b64 s[20:21], s[22:23]
	s_cbranch_scc0 .LBB0_243
	s_setprio 0
	s_and_b64 vcc, exec, s[10:11]
	s_cbranch_vccz .LBB0_246
	s_barrier

; #define PG8_STAGE(bufoff, gbase, voff) do { _Pragma("unroll") for (int _i = 0; _i < 2; ++_i) \
;         __builtin_amdgcn_global_load_lds((const unsigned*)((const char*)(gbase) + (voff)[_i]), (LAS unsigned*)(lds + (bufoff) + ldsw + _i * 8192), 16, 0, 0); } while (0)
; #define PG8_LDA(dst, b, h) do { _Pragma("unroll") for (int m = 0; m < 4; ++m) _Pragma("unroll") for (int k = 0; k < 2; ++k) dst[m][k] = *(const LAS bf16x8*)(lds + PG8_SA(b, h) + aoff + m * 2048 + k * 1024); } while (0)
; #define PG8_LDB(dst, b, h) do { _Pragma("unroll") for (int n = 0; n < 2; ++n) _Pragma("unroll") for (int k = 0; k < 2; ++k) dst[n][k] = *(const LAS bf16x8*)(lds + PG8_SB(b, h) + boff + n * 2048 + k * 1024); } while (0)
; #define PG8_MMA(ai, bj, At, Bt) do { __builtin_amdgcn_s_setprio(1); _Pragma("unroll") for (int m = 0; m < 4; ++m) _Pragma("unroll") for (int n = 0; n < 2; ++n) _Pragma("unroll") for (int k = 0; k < 2; ++k) \
;         acc[ai][bj][m][n] = __builtin_amdgcn_mfma_f32_16x16x32_bf16(Bt[n][k], At[m][k], acc[ai][bj][m][n], 0, 0, 0); __builtin_amdgcn_s_setprio(0); } while (0)
; #define PG8_WAIT_V(n) asm volatile("s_waitcnt vmcnt(" #n ")" ::: "memory")
; #define PG8_WAIT_L(n) asm volatile("s_waitcnt lgkmcnt(" #n ")" ::: "memory")
; #define PG8_BAR __builtin_amdgcn_s_barrier()
; #define PG8_SCHED __builtin_amdgcn_sched_barrier(0)
; template <class Sched, class Epi, bool ALIGN_EPI, bool SP2>
; __device__ __forceinline__ void gemm_phase(LAS unsigned char* lds, const int K, const int lda, const int ldb, const Sched& S, const Epi& E) {
;     ...
;             PG8_LDB(B0, 0, 0); PG8_LDB(B1, 0, 1); PG8_SCHED; PG8_LDA(At, 0, 0); PG8_STAGE(PG8_SA(1, 1), a1 + hstepA, voffA);
;             PG8_WAIT_V(8); PG8_WAIT_L(0); PG8_BAR; PG8_MMA(0, 0, At, B0); PG8_MMA(0, 1, At, B1); PG8_BAR; PG8_SCHED;
;             PG8_LDA(At, 0, 1); PG8_STAGE(PG8_SB(0, 0), b2, voffB); PG8_STAGE(PG8_SB(0, 1), b2 + hstepB, voffB); PG8_STAGE(PG8_SA(0, 0), a2, voffA);
;             PG8_WAIT_V(8); PG8_WAIT_L(0); PG8_BAR; PG8_MMA(1, 0, At, B0); PG8_MMA(1, 1, At, B1); PG8_BAR; PG8_SCHED;
.Lprio_skip_353:
.LBB0_353:
	s_waitcnt lgkmcnt(0)
	ds_read_b128 v[32:35], v211
	ds_read_b128 v[36:39], v211 offset:1024
	ds_read_b128 v[48:51], v211 offset:2048
	ds_read_b128 v[52:55], v211 offset:3072
	ds_read_b128 v[56:59], v212
	ds_read_b128 v[60:63], v212 offset:1024
	ds_read_b128 v[64:67], v212 offset:2048
	ds_read_b128 v[68:71], v212 offset:3072
	s_add_u32 s8, s26, 0xfff80080
	s_addc_u32 s9, s27, -1
	s_cmp_eq_u32 s7, 28
	s_cselect_b32 s37, s1, s9
	s_cselect_b32 s36, s4, s8
	s_cselect_b32 s29, s21, s6
	s_cselect_b32 s28, vcc_lo, vcc_hi
	s_add_i32 m0, s89, 0xc000
	ds_read_b128 v[76:79], v213
	ds_read_b128 v[80:83], v213 offset:1024
	ds_read_b128 v[88:91], v213 offset:2048
	ds_read_b128 v[92:95], v213 offset:3072
	ds_read_b128 v[196:199], v213 offset:4096
	ds_read_b128 v[200:203], v213 offset:5120
	ds_read_b128 v[204:207], v213 offset:6144
	ds_read_b128 v[216:219], v213 offset:7168
	global_load_lds_dwordx4 v192, s[26:27]
	s_add_i32 m0, s89, 0xe000
	s_nop 0
	global_load_lds_dwordx4 v194, s[26:27]
	s_waitcnt vmcnt(8) lgkmcnt(0)
	s_barrier
	v_mfma_f32_16x16x32_bf16 v[172:175], v[32:35], v[76:79], v[172:175]
	v_mfma_f32_16x16x32_bf16 v[168:171], v[48:51], v[76:79], v[168:171]
	v_mfma_f32_16x16x32_bf16 v[156:159], v[32:35], v[88:91], v[156:159]
	v_mfma_f32_16x16x32_bf16 v[152:155], v[48:51], v[88:91], v[152:155]
	v_mfma_f32_16x16x32_bf16 v[140:143], v[32:35], v[196:199], v[140:143]
	v_mfma_f32_16x16x32_bf16 v[136:139], v[48:51], v[196:199], v[136:139]
	v_mfma_f32_16x16x32_bf16 v[124:127], v[32:35], v[204:207], v[124:127]
	v_mfma_f32_16x16x32_bf16 v[120:123], v[48:51], v[204:207], v[120:123]
	v_mfma_f32_16x16x32_bf16 v[172:175], v[36:39], v[80:83], v[172:175]
	v_mfma_f32_16x16x32_bf16 v[168:171], v[52:55], v[80:83], v[168:171]
	v_mfma_f32_16x16x32_bf16 v[156:159], v[36:39], v[92:95], v[156:159]
	v_mfma_f32_16x16x32_bf16 v[152:155], v[52:55], v[92:95], v[152:155]
	v_mfma_f32_16x16x32_bf16 v[140:143], v[36:39], v[200:203], v[140:143]
	v_mfma_f32_16x16x32_bf16 v[136:139], v[52:55], v[200:203], v[136:139]
	v_mfma_f32_16x16x32_bf16 v[124:127], v[36:39], v[216:219], v[124:127]
	v_mfma_f32_16x16x32_bf16 v[120:123], v[52:55], v[216:219], v[120:123]
	v_mfma_f32_16x16x32_bf16 v[164:167], v[56:59], v[76:79], v[164:167]
	v_mfma_f32_16x16x32_bf16 v[76:79], v[64:67], v[76:79], v[160:163]
	v_mfma_f32_16x16x32_bf16 v[164:167], v[60:63], v[80:83], v[164:167]
	v_mfma_f32_16x16x32_bf16 v[76:79], v[68:71], v[80:83], v[76:79]
	v_mfma_f32_16x16x32_bf16 v[80:83], v[56:59], v[88:91], v[148:151]
	v_mfma_f32_16x16x32_bf16 v[88:91], v[64:67], v[88:91], v[144:147]
	v_mfma_f32_16x16x32_bf16 v[128:131], v[64:67], v[196:199], v[128:131]
	v_mfma_f32_16x16x32_bf16 v[116:119], v[56:59], v[204:207], v[116:119]
	v_mfma_f32_16x16x32_bf16 v[112:115], v[64:67], v[204:207], v[112:115]
	v_mfma_f32_16x16x32_bf16 v[80:83], v[60:63], v[92:95], v[80:83]
	v_mfma_f32_16x16x32_bf16 v[88:91], v[68:71], v[92:95], v[88:91]
	v_mfma_f32_16x16x32_bf16 v[92:95], v[56:59], v[196:199], v[132:135]
	v_mfma_f32_16x16x32_bf16 v[128:131], v[68:71], v[200:203], v[128:131]
	v_mfma_f32_16x16x32_bf16 v[116:119], v[60:63], v[216:219], v[116:119]
	v_mfma_f32_16x16x32_bf16 v[112:115], v[68:71], v[216:219], v[112:115]
	v_mfma_f32_16x16x32_bf16 v[92:95], v[60:63], v[200:203], v[92:95]
	s_barrier
	s_add_i32 s8, s85, s88
	v_lshl_add_u64 v[208:209], s[28:29], 0, v[186:187]
	s_mov_b32 m0, s8
	ds_read_b128 v[132:135], v213 offset:16384
	ds_read_b128 v[144:147], v213 offset:17408
	ds_read_b128 v[148:151], v213 offset:18432
	ds_read_b128 v[160:163], v213 offset:19456
	ds_read_b128 v[196:199], v213 offset:20480
	ds_read_b128 v[200:203], v213 offset:21504
	ds_read_b128 v[204:207], v213 offset:22528
	ds_read_b128 v[216:219], v213 offset:23552
	global_load_lds_dwordx4 v[208:209], off
	s_add_i32 m0, s8, 0x2000
	s_add_u32 s8, s28, 0x80000
	v_lshl_add_u64 v[228:229], s[28:29], 0, v[190:191]
	s_addc_u32 s9, s29, 0
	s_add_i32 s51, s50, s88
	global_load_lds_dwordx4 v[228:229], off
	s_mov_b32 m0, s51
	v_lshl_add_u64 v[230:231], s[36:37], 0, v[184:185]
	global_load_lds_dwordx4 v186, s[8:9]
	s_add_i32 m0, s51, 0x2000
	v_lshl_add_u64 v[232:233], s[36:37], 0, v[188:189]
	global_load_lds_dwordx4 v190, s[8:9]
	s_mov_b32 m0, s89
	s_nop 0
	global_load_lds_dwordx4 v[230:231], off
	s_mov_b32 m0, s90
	s_nop 0
	global_load_lds_dwordx4 v[232:233], off
	s_waitcnt vmcnt(8) lgkmcnt(0)
	s_barrier
	v_mfma_f32_16x16x32_bf16 v[108:111], v[32:35], v[132:135], v[108:111]
	v_mfma_f32_16x16x32_bf16 v[104:107], v[48:51], v[132:135], v[104:107]
	v_mfma_f32_16x16x32_bf16 v[84:87], v[32:35], v[148:151], v[84:87]
	v_mfma_f32_16x16x32_bf16 v[72:75], v[48:51], v[148:151], v[72:75]
	v_mfma_f32_16x16x32_bf16 v[28:31], v[32:35], v[196:199], v[28:31]
	v_mfma_f32_16x16x32_bf16 v[24:27], v[48:51], v[196:199], v[24:27]
	v_mfma_f32_16x16x32_bf16 v[12:15], v[32:35], v[204:207], v[12:15]
	v_mfma_f32_16x16x32_bf16 v[8:11], v[48:51], v[204:207], v[8:11]
	v_mfma_f32_16x16x32_bf16 v[108:111], v[36:39], v[144:147], v[108:111]
	v_mfma_f32_16x16x32_bf16 v[104:107], v[52:55], v[144:147], v[104:107]
	v_mfma_f32_16x16x32_bf16 v[84:87], v[36:39], v[160:163], v[84:87]
	v_mfma_f32_16x16x32_bf16 v[72:75], v[52:55], v[160:163], v[72:75]
	v_mfma_f32_16x16x32_bf16 v[28:31], v[36:39], v[200:203], v[28:31]
	v_mfma_f32_16x16x32_bf16 v[24:27], v[52:55], v[200:203], v[24:27]
	v_mfma_f32_16x16x32_bf16 v[12:15], v[36:39], v[216:219], v[12:15]
	v_mfma_f32_16x16x32_bf16 v[8:11], v[52:55], v[216:219], v[8:11]
	v_mfma_f32_16x16x32_bf16 v[44:47], v[56:59], v[148:151], v[44:47]
	v_mfma_f32_16x16x32_bf16 v[40:43], v[64:67], v[148:151], v[40:43]
	v_mfma_f32_16x16x32_bf16 v[20:23], v[56:59], v[196:199], v[20:23]
	v_mfma_f32_16x16x32_bf16 v[16:19], v[64:67], v[196:199], v[16:19]
	v_mfma_f32_16x16x32_bf16 v[4:7], v[56:59], v[204:207], v[4:7]
	v_mfma_f32_16x16x32_bf16 v[0:3], v[64:67], v[204:207], v[0:3]
	v_mfma_f32_16x16x32_bf16 v[32:35], v[56:59], v[132:135], v[100:103]
	v_mfma_f32_16x16x32_bf16 v[36:39], v[64:67], v[132:135], v[96:99]
	v_mfma_f32_16x16x32_bf16 v[44:47], v[60:63], v[160:163], v[44:47]
	v_mfma_f32_16x16x32_bf16 v[40:43], v[68:71], v[160:163], v[40:43]
	v_mfma_f32_16x16x32_bf16 v[20:23], v[60:63], v[200:203], v[20:23]
	v_mfma_f32_16x16x32_bf16 v[16:19], v[68:71], v[200:203], v[16:19]
	v_mfma_f32_16x16x32_bf16 v[4:7], v[60:63], v[216:219], v[4:7]
	v_mfma_f32_16x16x32_bf16 v[0:3], v[68:71], v[216:219], v[0:3]
	v_mfma_f32_16x16x32_bf16 v[32:35], v[60:63], v[144:147], v[32:35]
	v_mfma_f32_16x16x32_bf16 v[36:39], v[68:71], v[144:147], v[36:39]
	s_barrier
; #define PG8_STAGE(bufoff, gbase, voff) do { _Pragma("unroll") for (int _i = 0; _i < 2; ++_i) \
;         __builtin_amdgcn_global_load_lds((const unsigned*)((const char*)(gbase) + (voff)[_i]), (LAS unsigned*)(lds + (bufoff) + ldsw + _i * 8192), 16, 0, 0); } while (0)
; #define PG8_LDA(dst, b, h) do { _Pragma("unroll") for (int m = 0; m < 4; ++m) _Pragma("unroll") for (int k = 0; k < 2; ++k) dst[m][k] = *(const LAS bf16x8*)(lds + PG8_SA(b, h) + aoff + m * 2048 + k * 1024); } while (0)
; #define PG8_LDB(dst, b, h) do { _Pragma("unroll") for (int n = 0; n < 2; ++n) _Pragma("unroll") for (int k = 0; k < 2; ++k) dst[n][k] = *(const LAS bf16x8*)(lds + PG8_SB(b, h) + boff + n * 2048 + k * 1024); } while (0)
; #define PG8_MMA(ai, bj, At, Bt) do { __builtin_amdgcn_s_setprio(1); _Pragma("unroll") for (int m = 0; m < 4; ++m) _Pragma("unroll") for (int n = 0; n < 2; ++n) _Pragma("unroll") for (int k = 0; k < 2; ++k) \
;         acc[ai][bj][m][n] = __builtin_amdgcn_mfma_f32_16x16x32_bf16(Bt[n][k], At[m][k], acc[ai][bj][m][n], 0, 0, 0); __builtin_amdgcn_s_setprio(0); } while (0)
; #define PG8_WAIT_V(n) asm volatile("s_waitcnt vmcnt(" #n ")" ::: "memory")
; #define PG8_WAIT_L(n) asm volatile("s_waitcnt lgkmcnt(" #n ")" ::: "memory")
; #define PG8_BAR __builtin_amdgcn_s_barrier()
; #define PG8_SCHED __builtin_amdgcn_sched_barrier(0)
; template <class Sched, class Epi, bool ALIGN_EPI, bool SP2>
; __device__ __forceinline__ void gemm_phase(LAS unsigned char* lds, const int K, const int lda, const int ldb, const Sched& S, const Epi& E) {
;     ...
;             PG8_LDB(B0, 1, 0); PG8_LDB(B1, 1, 1); PG8_SCHED; PG8_LDA(At, 1, 0); PG8_STAGE(PG8_SA(0, 1), a2 + hstepA, voffA);
;             PG8_WAIT_V(8); PG8_WAIT_L(0); PG8_BAR; PG8_MMA(0, 0, At, B0); PG8_MMA(0, 1, At, B1); PG8_BAR; PG8_SCHED;
;             PG8_LDA(At, 1, 1); PG8_STAGE(PG8_SB(1, 0), b3, voffB); PG8_STAGE(PG8_SB(1, 1), b3 + hstepB, voffB); PG8_STAGE(PG8_SA(1, 0), a3, voffA);
;             PG8_WAIT_V(8); PG8_WAIT_L(0); PG8_BAR; PG8_MMA(1, 0, At, B0); PG8_MMA(1, 1, At, B1); PG8_BAR; PG8_SCHED;
	s_add_i32 s51, 0, 0x18000
	s_add_i32 s17, 0, 0x1c000
	v_add_u32_e32 v60, s51, v183
	v_add_u32_e32 v96, s17, v183
	ds_read_b128 v[48:51], v60
	ds_read_b128 v[52:55], v60 offset:1024
	ds_read_b128 v[56:59], v60 offset:2048
	ds_read_b128 v[60:63], v60 offset:3072
	ds_read_b128 v[64:67], v96
	ds_read_b128 v[68:71], v96 offset:1024
	ds_read_b128 v[196:199], v96 offset:2048
	ds_read_b128 v[200:203], v96 offset:3072
	s_add_u32 s8, s36, 0x80000
	s_addc_u32 s9, s37, 0
	s_mov_b32 m0, s91
	ds_read_b128 v[96:99], v213 offset:32768
	ds_read_b128 v[100:103], v213 offset:33792
	ds_read_b128 v[132:135], v213 offset:34816
	ds_read_b128 v[144:147], v213 offset:35840
	ds_read_b128 v[204:207], v213 offset:36864
	ds_read_b128 v[216:219], v213 offset:37888
	ds_read_b128 v[220:223], v213 offset:38912
	ds_read_b128 v[224:227], v213 offset:39936
	global_load_lds_dwordx4 v184, s[8:9]
	s_mov_b32 m0, s96
	s_nop 0
	global_load_lds_dwordx4 v188, s[8:9]
	s_waitcnt vmcnt(8) lgkmcnt(0)
	s_barrier
	v_mfma_f32_16x16x32_bf16 v[148:151], v[48:51], v[96:99], v[172:175]
	v_mfma_f32_16x16x32_bf16 v[172:175], v[52:55], v[100:103], v[148:151]
	v_mfma_f32_16x16x32_bf16 v[148:151], v[56:59], v[96:99], v[168:171]
	v_mfma_f32_16x16x32_bf16 v[168:171], v[60:63], v[100:103], v[148:151]
	v_mfma_f32_16x16x32_bf16 v[148:151], v[48:51], v[132:135], v[156:159]
	v_mfma_f32_16x16x32_bf16 v[156:159], v[52:55], v[144:147], v[148:151]
	v_mfma_f32_16x16x32_bf16 v[148:151], v[56:59], v[132:135], v[152:155]
	v_mfma_f32_16x16x32_bf16 v[140:143], v[48:51], v[204:207], v[140:143]
	v_mfma_f32_16x16x32_bf16 v[136:139], v[56:59], v[204:207], v[136:139]
	v_mfma_f32_16x16x32_bf16 v[124:127], v[48:51], v[220:223], v[124:127]
	v_mfma_f32_16x16x32_bf16 v[120:123], v[56:59], v[220:223], v[120:123]
	v_mfma_f32_16x16x32_bf16 v[152:155], v[60:63], v[144:147], v[148:151]
	v_mfma_f32_16x16x32_bf16 v[140:143], v[52:55], v[216:219], v[140:143]
	v_mfma_f32_16x16x32_bf16 v[136:139], v[60:63], v[216:219], v[136:139]
	v_mfma_f32_16x16x32_bf16 v[124:127], v[52:55], v[224:227], v[124:127]
	v_mfma_f32_16x16x32_bf16 v[120:123], v[60:63], v[224:227], v[120:123]
	v_mfma_f32_16x16x32_bf16 v[76:79], v[196:199], v[96:99], v[76:79]
	v_mfma_f32_16x16x32_bf16 v[148:151], v[64:67], v[96:99], v[164:167]
	v_mfma_f32_16x16x32_bf16 v[160:163], v[200:203], v[100:103], v[76:79]
	v_mfma_f32_16x16x32_bf16 v[76:79], v[64:67], v[132:135], v[80:83]
	v_mfma_f32_16x16x32_bf16 v[164:167], v[68:71], v[100:103], v[148:151]
	v_mfma_f32_16x16x32_bf16 v[148:151], v[68:71], v[144:147], v[76:79]
	v_mfma_f32_16x16x32_bf16 v[76:79], v[196:199], v[132:135], v[88:91]
	v_mfma_f32_16x16x32_bf16 v[144:147], v[200:203], v[144:147], v[76:79]
	v_mfma_f32_16x16x32_bf16 v[76:79], v[64:67], v[204:207], v[92:95]
	v_mfma_f32_16x16x32_bf16 v[132:135], v[68:71], v[216:219], v[76:79]
	v_mfma_f32_16x16x32_bf16 v[76:79], v[196:199], v[204:207], v[128:131]
	v_mfma_f32_16x16x32_bf16 v[128:131], v[200:203], v[216:219], v[76:79]
	v_mfma_f32_16x16x32_bf16 v[76:79], v[64:67], v[220:223], v[116:119]
	v_mfma_f32_16x16x32_bf16 v[116:119], v[68:71], v[224:227], v[76:79]
	v_mfma_f32_16x16x32_bf16 v[76:79], v[196:199], v[220:223], v[112:115]
	v_mfma_f32_16x16x32_bf16 v[112:115], v[200:203], v[224:227], v[76:79]
	s_barrier
	s_add_i32 s8, s51, s88
	v_lshl_add_u64 v[96:97], v[208:209], 0, s[10:11]
	s_mov_b32 m0, s8
	s_nop 1
	ds_read_b128 v[76:79], v213 offset:49152
	ds_read_b128 v[80:83], v213 offset:50176
	ds_read_b128 v[88:91], v213 offset:51200
	ds_read_b128 v[92:95], v213 offset:52224
	ds_read_b128 v[204:207], v213 offset:53248
	ds_read_b128 v[216:219], v213 offset:54272
	ds_read_b128 v[220:223], v213 offset:55296
	ds_read_b128 v[224:227], v213 offset:56320
	global_load_lds_dwordx4 v[96:97], off
	s_add_i32 m0, s8, 0x2000
	s_add_u32 s8, s28, 0x80080
	v_lshl_add_u64 v[96:97], v[228:229], 0, s[10:11]
	s_addc_u32 s9, s29, 0
	s_add_i32 s17, s17, s88
	global_load_lds_dwordx4 v[96:97], off
	s_mov_b32 m0, s17
	s_nop 0
	global_load_lds_dwordx4 v186, s[8:9]
	s_add_i32 m0, s17, 0x2000
	s_nop 0
	global_load_lds_dwordx4 v190, s[8:9]
	v_lshl_add_u64 v[96:97], v[230:231], 0, s[10:11]
	s_mov_b32 m0, s97
	s_nop 0
	global_load_lds_dwordx4 v[96:97], off
	v_lshl_add_u64 v[96:97], v[232:233], 0, s[10:11]
	s_mov_b32 m0, s84
	s_nop 0
	global_load_lds_dwordx4 v[96:97], off
	s_waitcnt vmcnt(8) lgkmcnt(0)
	s_barrier
	v_mfma_f32_16x16x32_bf16 v[96:99], v[48:51], v[76:79], v[108:111]
	v_mfma_f32_16x16x32_bf16 v[108:111], v[52:55], v[80:83], v[96:99]
	v_mfma_f32_16x16x32_bf16 v[96:99], v[56:59], v[76:79], v[104:107]
	v_mfma_f32_16x16x32_bf16 v[84:87], v[48:51], v[88:91], v[84:87]
	v_mfma_f32_16x16x32_bf16 v[72:75], v[56:59], v[88:91], v[72:75]
	v_mfma_f32_16x16x32_bf16 v[28:31], v[48:51], v[204:207], v[28:31]
	v_mfma_f32_16x16x32_bf16 v[24:27], v[56:59], v[204:207], v[24:27]
	v_mfma_f32_16x16x32_bf16 v[12:15], v[48:51], v[220:223], v[12:15]
	v_mfma_f32_16x16x32_bf16 v[8:11], v[56:59], v[220:223], v[8:11]
	v_mfma_f32_16x16x32_bf16 v[104:107], v[60:63], v[80:83], v[96:99]
	v_mfma_f32_16x16x32_bf16 v[84:87], v[52:55], v[92:95], v[84:87]
	v_mfma_f32_16x16x32_bf16 v[72:75], v[60:63], v[92:95], v[72:75]
	v_mfma_f32_16x16x32_bf16 v[28:31], v[52:55], v[216:219], v[28:31]
	v_mfma_f32_16x16x32_bf16 v[24:27], v[60:63], v[216:219], v[24:27]
	v_mfma_f32_16x16x32_bf16 v[12:15], v[52:55], v[224:227], v[12:15]
	v_mfma_f32_16x16x32_bf16 v[8:11], v[60:63], v[224:227], v[8:11]
	v_mfma_f32_16x16x32_bf16 v[32:35], v[64:67], v[76:79], v[32:35]
	v_mfma_f32_16x16x32_bf16 v[100:103], v[68:71], v[80:83], v[32:35]
	v_mfma_f32_16x16x32_bf16 v[32:35], v[196:199], v[76:79], v[36:39]
	v_mfma_f32_16x16x32_bf16 v[96:99], v[200:203], v[80:83], v[32:35]
	v_mfma_f32_16x16x32_bf16 v[32:35], v[64:67], v[88:91], v[44:47]
	v_mfma_f32_16x16x32_bf16 v[44:47], v[68:71], v[92:95], v[32:35]
	v_mfma_f32_16x16x32_bf16 v[32:35], v[196:199], v[88:91], v[40:43]
	v_mfma_f32_16x16x32_bf16 v[20:23], v[64:67], v[204:207], v[20:23]
	v_mfma_f32_16x16x32_bf16 v[16:19], v[196:199], v[204:207], v[16:19]
	v_mfma_f32_16x16x32_bf16 v[4:7], v[64:67], v[220:223], v[4:7]
	v_mfma_f32_16x16x32_bf16 v[0:3], v[196:199], v[220:223], v[0:3]
	v_mfma_f32_16x16x32_bf16 v[40:43], v[200:203], v[92:95], v[32:35]
	v_mfma_f32_16x16x32_bf16 v[20:23], v[68:71], v[216:219], v[20:23]
	v_mfma_f32_16x16x32_bf16 v[16:19], v[200:203], v[216:219], v[16:19]
	v_mfma_f32_16x16x32_bf16 v[4:7], v[68:71], v[224:227], v[4:7]
	v_mfma_f32_16x16x32_bf16 v[0:3], v[200:203], v[224:227], v[0:3]
	s_barrier
	s_add_i32 s7, s7, 2
	s_add_u32 s26, s26, 0x100
	s_addc_u32 s27, s27, 0
	s_add_u32 vcc_hi, vcc_hi, 0x100
	s_addc_u32 s6, s6, 0
	s_cmp_gt_u32 s7, 29
	s_cbranch_scc0 .LBB0_353
	s_setprio 0
	s_and_b64 vcc, exec, s[12:13]
	s_cbranch_vccz .LBB0_356
	s_barrier

; #define PG8_STAGE(bufoff, gbase, voff) do { _Pragma("unroll") for (int _i = 0; _i < 2; ++_i) \
;         __builtin_amdgcn_global_load_lds((const unsigned*)((const char*)(gbase) + (voff)[_i]), (LAS unsigned*)(lds + (bufoff) + ldsw + _i * 8192), 16, 0, 0); } while (0)
; #define PG8_LDA(dst, b, h) do { _Pragma("unroll") for (int m = 0; m < 4; ++m) _Pragma("unroll") for (int k = 0; k < 2; ++k) dst[m][k] = *(const LAS bf16x8*)(lds + PG8_SA(b, h) + aoff + m * 2048 + k * 1024); } while (0)
; #define PG8_LDB(dst, b, h) do { _Pragma("unroll") for (int n = 0; n < 2; ++n) _Pragma("unroll") for (int k = 0; k < 2; ++k) dst[n][k] = *(const LAS bf16x8*)(lds + PG8_SB(b, h) + boff + n * 2048 + k * 1024); } while (0)
; #define PG8_MMA(ai, bj, At, Bt) do { __builtin_amdgcn_s_setprio(1); _Pragma("unroll") for (int m = 0; m < 4; ++m) _Pragma("unroll") for (int n = 0; n < 2; ++n) _Pragma("unroll") for (int k = 0; k < 2; ++k) \
;         acc[ai][bj][m][n] = __builtin_amdgcn_mfma_f32_16x16x32_bf16(Bt[n][k], At[m][k], acc[ai][bj][m][n], 0, 0, 0); __builtin_amdgcn_s_setprio(0); } while (0)
; #define PG8_WAIT_V(n) asm volatile("s_waitcnt vmcnt(" #n ")" ::: "memory")
; #define PG8_WAIT_L(n) asm volatile("s_waitcnt lgkmcnt(" #n ")" ::: "memory")
; #define PG8_BAR __builtin_amdgcn_s_barrier()
; #define PG8_SCHED __builtin_amdgcn_sched_barrier(0)
; template <class Sched, class Epi, bool ALIGN_EPI, bool SP2>
; __device__ __forceinline__ void gemm_phase(LAS unsigned char* lds, const int K, const int lda, const int ldb, const Sched& S, const Epi& E) {
;     ...
;             PG8_LDB(B0, 0, 0); PG8_LDB(B1, 0, 1); PG8_SCHED; PG8_LDA(At, 0, 0); PG8_STAGE(PG8_SA(1, 1), a1 + hstepA, voffA);
;             PG8_WAIT_V(8); PG8_WAIT_L(0); PG8_BAR; PG8_MMA(0, 0, At, B0); PG8_MMA(0, 1, At, B1); PG8_BAR; PG8_SCHED;
;             PG8_LDA(At, 0, 1); PG8_STAGE(PG8_SB(0, 0), b2, voffB); PG8_STAGE(PG8_SB(0, 1), b2 + hstepB, voffB); PG8_STAGE(PG8_SA(0, 0), a2, voffA);
;             PG8_WAIT_V(8); PG8_WAIT_L(0); PG8_BAR; PG8_MMA(1, 0, At, B0); PG8_MMA(1, 1, At, B1); PG8_BAR; PG8_SCHED;
.Lprio_skip_821:
.LBB0_821:
	v_add_u32_e32 v140, s44, v181
	v_add_u32_e32 v170, s45, v181
	ds_read_b128 v[128:131], v140
	ds_read_b128 v[132:135], v140 offset:1024
	ds_read_b128 v[136:139], v140 offset:2048
	ds_read_b128 v[140:143], v140 offset:3072
	ds_read_b128 v[144:147], v170
	ds_read_b128 v[148:151], v170 offset:1024
	ds_read_b128 v[166:169], v170 offset:2048
	ds_read_b128 v[170:173], v170 offset:3072
	s_add_u32 s20, s4, 0x100
	s_addc_u32 s21, s5, 0
	s_cmp_eq_u32 s61, 12
	s_cselect_b32 s25, s15, s21
	s_cselect_b32 s24, s14, s20
	s_cselect_b32 s23, s17, s60
	s_cselect_b32 s22, s16, s53
	s_add_i32 m0, s29, 0xc000
	ds_read_b128 v[184:187], v183
	ds_read_b128 v[188:191], v183 offset:1024
	ds_read_b128 v[192:195], v183 offset:2048
	ds_read_b128 v[196:199], v183 offset:3072
	ds_read_b128 v[200:203], v183 offset:4096
	ds_read_b128 v[204:207], v183 offset:5120
	ds_read_b128 v[208:211], v183 offset:6144
	ds_read_b128 v[212:215], v183 offset:7168
	global_load_lds_dwordx4 v162, s[4:5]
	s_add_i32 m0, s29, 0xe000
	s_nop 0
	global_load_lds_dwordx4 v164, s[4:5]
	s_waitcnt vmcnt(8) lgkmcnt(0)
	s_barrier
	v_mfma_f32_16x16x32_bf16 v[124:127], v[128:131], v[184:187], v[124:127]
	v_mfma_f32_16x16x32_bf16 v[120:123], v[136:139], v[184:187], v[120:123]
	v_mfma_f32_16x16x32_bf16 v[116:119], v[128:131], v[192:195], v[116:119]
	v_mfma_f32_16x16x32_bf16 v[112:115], v[136:139], v[192:195], v[112:115]
	v_mfma_f32_16x16x32_bf16 v[108:111], v[128:131], v[200:203], v[108:111]
	v_mfma_f32_16x16x32_bf16 v[104:107], v[136:139], v[200:203], v[104:107]
	v_mfma_f32_16x16x32_bf16 v[100:103], v[128:131], v[208:211], v[100:103]
	v_mfma_f32_16x16x32_bf16 v[96:99], v[136:139], v[208:211], v[96:99]
	v_mfma_f32_16x16x32_bf16 v[124:127], v[132:135], v[188:191], v[124:127]
	v_mfma_f32_16x16x32_bf16 v[120:123], v[140:143], v[188:191], v[120:123]
	v_mfma_f32_16x16x32_bf16 v[116:119], v[132:135], v[196:199], v[116:119]
	v_mfma_f32_16x16x32_bf16 v[112:115], v[140:143], v[196:199], v[112:115]
	v_mfma_f32_16x16x32_bf16 v[108:111], v[132:135], v[204:207], v[108:111]
	v_mfma_f32_16x16x32_bf16 v[104:107], v[140:143], v[204:207], v[104:107]
	v_mfma_f32_16x16x32_bf16 v[100:103], v[132:135], v[212:215], v[100:103]
	v_mfma_f32_16x16x32_bf16 v[96:99], v[140:143], v[212:215], v[96:99]
	v_mfma_f32_16x16x32_bf16 v[92:95], v[144:147], v[184:187], v[92:95]
	v_mfma_f32_16x16x32_bf16 v[88:91], v[166:169], v[184:187], v[88:91]
	v_mfma_f32_16x16x32_bf16 v[84:87], v[144:147], v[192:195], v[84:87]
	v_mfma_f32_16x16x32_bf16 v[80:83], v[166:169], v[192:195], v[80:83]
	v_mfma_f32_16x16x32_bf16 v[76:79], v[144:147], v[200:203], v[76:79]
	v_mfma_f32_16x16x32_bf16 v[72:75], v[166:169], v[200:203], v[72:75]
	v_mfma_f32_16x16x32_bf16 v[68:71], v[144:147], v[208:211], v[68:71]
	v_mfma_f32_16x16x32_bf16 v[64:67], v[166:169], v[208:211], v[64:67]
	v_mfma_f32_16x16x32_bf16 v[92:95], v[148:151], v[188:191], v[92:95]
	v_mfma_f32_16x16x32_bf16 v[88:91], v[170:173], v[188:191], v[88:91]
	v_mfma_f32_16x16x32_bf16 v[84:87], v[148:151], v[196:199], v[84:87]
	v_mfma_f32_16x16x32_bf16 v[80:83], v[170:173], v[196:199], v[80:83]
	v_mfma_f32_16x16x32_bf16 v[76:79], v[148:151], v[204:207], v[76:79]
	v_mfma_f32_16x16x32_bf16 v[72:75], v[170:173], v[204:207], v[72:75]
	v_mfma_f32_16x16x32_bf16 v[68:71], v[148:151], v[212:215], v[68:71]
	v_mfma_f32_16x16x32_bf16 v[64:67], v[170:173], v[212:215], v[64:67]
	s_barrier
	s_add_i32 s4, s44, s28
	v_lshl_add_u64 v[174:175], s[22:23], 0, v[156:157]
	s_mov_b32 m0, s4
	ds_read_b128 v[184:187], v183 offset:16384
	ds_read_b128 v[188:191], v183 offset:17408
	ds_read_b128 v[192:195], v183 offset:18432
	ds_read_b128 v[196:199], v183 offset:19456
	ds_read_b128 v[200:203], v183 offset:20480
	ds_read_b128 v[204:207], v183 offset:21504
	ds_read_b128 v[208:211], v183 offset:22528
	ds_read_b128 v[212:215], v183 offset:23552
	global_load_lds_dwordx4 v[174:175], off
	s_add_i32 m0, s4, 0x2000
	s_add_u32 s4, s22, 0x40000
	v_lshl_add_u64 v[216:217], s[22:23], 0, v[160:161]
	s_addc_u32 s5, s23, 0
	s_add_i32 s62, s45, s28
	global_load_lds_dwordx4 v[216:217], off
	s_mov_b32 m0, s62
	v_lshl_add_u64 v[220:221], s[24:25], 0, v[158:159]
	global_load_lds_dwordx4 v156, s[4:5]
	s_add_i32 m0, s62, 0x2000
	s_nop 0
	global_load_lds_dwordx4 v160, s[4:5]
	v_lshl_add_u64 v[218:219], s[24:25], 0, v[154:155]
	s_mov_b32 m0, s29
	s_nop 0
	global_load_lds_dwordx4 v[218:219], off
	s_mov_b32 m0, s33
	s_nop 0
	global_load_lds_dwordx4 v[220:221], off
	s_waitcnt vmcnt(8) lgkmcnt(0)
	s_barrier
	v_mfma_f32_16x16x32_bf16 v[60:63], v[128:131], v[184:187], v[60:63]
	v_mfma_f32_16x16x32_bf16 v[56:59], v[136:139], v[184:187], v[56:59]
	v_mfma_f32_16x16x32_bf16 v[52:55], v[128:131], v[192:195], v[52:55]
	v_mfma_f32_16x16x32_bf16 v[48:51], v[136:139], v[192:195], v[48:51]
	v_mfma_f32_16x16x32_bf16 v[44:47], v[128:131], v[200:203], v[44:47]
	v_mfma_f32_16x16x32_bf16 v[40:43], v[136:139], v[200:203], v[40:43]
	v_mfma_f32_16x16x32_bf16 v[36:39], v[128:131], v[208:211], v[36:39]
	v_mfma_f32_16x16x32_bf16 v[32:35], v[136:139], v[208:211], v[32:35]
	v_mfma_f32_16x16x32_bf16 v[60:63], v[132:135], v[188:191], v[60:63]
	v_mfma_f32_16x16x32_bf16 v[56:59], v[140:143], v[188:191], v[56:59]
	v_mfma_f32_16x16x32_bf16 v[52:55], v[132:135], v[196:199], v[52:55]
	v_mfma_f32_16x16x32_bf16 v[48:51], v[140:143], v[196:199], v[48:51]
	v_mfma_f32_16x16x32_bf16 v[44:47], v[132:135], v[204:207], v[44:47]
	v_mfma_f32_16x16x32_bf16 v[40:43], v[140:143], v[204:207], v[40:43]
	v_mfma_f32_16x16x32_bf16 v[36:39], v[132:135], v[212:215], v[36:39]
	v_mfma_f32_16x16x32_bf16 v[32:35], v[140:143], v[212:215], v[32:35]
	v_mfma_f32_16x16x32_bf16 v[28:31], v[144:147], v[184:187], v[28:31]
	v_mfma_f32_16x16x32_bf16 v[24:27], v[166:169], v[184:187], v[24:27]
	v_mfma_f32_16x16x32_bf16 v[20:23], v[144:147], v[192:195], v[20:23]
	v_mfma_f32_16x16x32_bf16 v[16:19], v[166:169], v[192:195], v[16:19]
	v_mfma_f32_16x16x32_bf16 v[12:15], v[144:147], v[200:203], v[12:15]
	v_mfma_f32_16x16x32_bf16 v[8:11], v[166:169], v[200:203], v[8:11]
	v_mfma_f32_16x16x32_bf16 v[4:7], v[144:147], v[208:211], v[4:7]
	v_mfma_f32_16x16x32_bf16 v[0:3], v[166:169], v[208:211], v[0:3]
	v_mfma_f32_16x16x32_bf16 v[28:31], v[148:151], v[188:191], v[28:31]
	v_mfma_f32_16x16x32_bf16 v[24:27], v[170:173], v[188:191], v[24:27]
	v_mfma_f32_16x16x32_bf16 v[20:23], v[148:151], v[196:199], v[20:23]
	v_mfma_f32_16x16x32_bf16 v[16:19], v[170:173], v[196:199], v[16:19]
	v_mfma_f32_16x16x32_bf16 v[12:15], v[148:151], v[204:207], v[12:15]
	v_mfma_f32_16x16x32_bf16 v[8:11], v[170:173], v[204:207], v[8:11]
	v_mfma_f32_16x16x32_bf16 v[4:7], v[148:151], v[212:215], v[4:7]
	v_mfma_f32_16x16x32_bf16 v[0:3], v[170:173], v[212:215], v[0:3]
	s_barrier
; #define PG8_STAGE(bufoff, gbase, voff) do { _Pragma("unroll") for (int _i = 0; _i < 2; ++_i) \
;         __builtin_amdgcn_global_load_lds((const unsigned*)((const char*)(gbase) + (voff)[_i]), (LAS unsigned*)(lds + (bufoff) + ldsw + _i * 8192), 16, 0, 0); } while (0)
; #define PG8_LDA(dst, b, h) do { _Pragma("unroll") for (int m = 0; m < 4; ++m) _Pragma("unroll") for (int k = 0; k < 2; ++k) dst[m][k] = *(const LAS bf16x8*)(lds + PG8_SA(b, h) + aoff + m * 2048 + k * 1024); } while (0)
; #define PG8_LDB(dst, b, h) do { _Pragma("unroll") for (int n = 0; n < 2; ++n) _Pragma("unroll") for (int k = 0; k < 2; ++k) dst[n][k] = *(const LAS bf16x8*)(lds + PG8_SB(b, h) + boff + n * 2048 + k * 1024); } while (0)
; #define PG8_MMA(ai, bj, At, Bt) do { __builtin_amdgcn_s_setprio(1); _Pragma("unroll") for (int m = 0; m < 4; ++m) _Pragma("unroll") for (int n = 0; n < 2; ++n) _Pragma("unroll") for (int k = 0; k < 2; ++k) \
;         acc[ai][bj][m][n] = __builtin_amdgcn_mfma_f32_16x16x32_bf16(Bt[n][k], At[m][k], acc[ai][bj][m][n], 0, 0, 0); __builtin_amdgcn_s_setprio(0); } while (0)
; #define PG8_WAIT_V(n) asm volatile("s_waitcnt vmcnt(" #n ")" ::: "memory")
; #define PG8_WAIT_L(n) asm volatile("s_waitcnt lgkmcnt(" #n ")" ::: "memory")
; #define PG8_BAR __builtin_amdgcn_s_barrier()
; #define PG8_SCHED __builtin_amdgcn_sched_barrier(0)
; template <class Sched, class Epi, bool ALIGN_EPI, bool SP2>
; __device__ __forceinline__ void gemm_phase(LAS unsigned char* lds, const int K, const int lda, const int ldb, const Sched& S, const Epi& E) {
;     ...
;             PG8_LDB(B0, 1, 0); PG8_LDB(B1, 1, 1); PG8_SCHED; PG8_LDA(At, 1, 0); PG8_STAGE(PG8_SA(0, 1), a2 + hstepA, voffA);
;             PG8_WAIT_V(8); PG8_WAIT_L(0); PG8_BAR; PG8_MMA(0, 0, At, B0); PG8_MMA(0, 1, At, B1); PG8_BAR; PG8_SCHED;
;             PG8_LDA(At, 1, 1); PG8_STAGE(PG8_SB(1, 0), b3, voffB); PG8_STAGE(PG8_SB(1, 1), b3 + hstepB, voffB); PG8_STAGE(PG8_SA(1, 0), a3, voffA);
;             PG8_WAIT_V(8); PG8_WAIT_L(0); PG8_BAR; PG8_MMA(1, 0, At, B0); PG8_MMA(1, 1, At, B1); PG8_BAR; PG8_SCHED;
	s_add_i32 s62, 0, 0x18000
	s_add_i32 s63, 0, 0x1c000
	v_add_u32_e32 v140, s62, v181
	v_add_u32_e32 v170, s63, v181
	ds_read_b128 v[128:131], v140
	ds_read_b128 v[132:135], v140 offset:1024
	ds_read_b128 v[136:139], v140 offset:2048
	ds_read_b128 v[140:143], v140 offset:3072
	ds_read_b128 v[144:147], v170
	ds_read_b128 v[148:151], v170 offset:1024
	ds_read_b128 v[166:169], v170 offset:2048
	ds_read_b128 v[170:173], v170 offset:3072
	s_add_u32 s4, s24, 0xc0000
	s_addc_u32 s5, s25, 0
	s_mov_b32 m0, s35
	ds_read_b128 v[184:187], v183 offset:32768
	ds_read_b128 v[188:191], v183 offset:33792
	ds_read_b128 v[192:195], v183 offset:34816
	ds_read_b128 v[196:199], v183 offset:35840
	ds_read_b128 v[200:203], v183 offset:36864
	ds_read_b128 v[204:207], v183 offset:37888
	ds_read_b128 v[208:211], v183 offset:38912
	ds_read_b128 v[212:215], v183 offset:39936
	global_load_lds_dwordx4 v154, s[4:5]
	s_mov_b32 m0, s36
	s_nop 0
	global_load_lds_dwordx4 v158, s[4:5]
	s_waitcnt vmcnt(8) lgkmcnt(0)
	s_barrier
	v_mfma_f32_16x16x32_bf16 v[124:127], v[128:131], v[184:187], v[124:127]
	v_mfma_f32_16x16x32_bf16 v[120:123], v[136:139], v[184:187], v[120:123]
	v_mfma_f32_16x16x32_bf16 v[116:119], v[128:131], v[192:195], v[116:119]
	v_mfma_f32_16x16x32_bf16 v[112:115], v[136:139], v[192:195], v[112:115]
	v_mfma_f32_16x16x32_bf16 v[108:111], v[128:131], v[200:203], v[108:111]
	v_mfma_f32_16x16x32_bf16 v[104:107], v[136:139], v[200:203], v[104:107]
	v_mfma_f32_16x16x32_bf16 v[100:103], v[128:131], v[208:211], v[100:103]
	v_mfma_f32_16x16x32_bf16 v[96:99], v[136:139], v[208:211], v[96:99]
	v_mfma_f32_16x16x32_bf16 v[124:127], v[132:135], v[188:191], v[124:127]
	v_mfma_f32_16x16x32_bf16 v[120:123], v[140:143], v[188:191], v[120:123]
	v_mfma_f32_16x16x32_bf16 v[116:119], v[132:135], v[196:199], v[116:119]
	v_mfma_f32_16x16x32_bf16 v[112:115], v[140:143], v[196:199], v[112:115]
	v_mfma_f32_16x16x32_bf16 v[108:111], v[132:135], v[204:207], v[108:111]
	v_mfma_f32_16x16x32_bf16 v[104:107], v[140:143], v[204:207], v[104:107]
	v_mfma_f32_16x16x32_bf16 v[100:103], v[132:135], v[212:215], v[100:103]
	v_mfma_f32_16x16x32_bf16 v[96:99], v[140:143], v[212:215], v[96:99]
	v_mfma_f32_16x16x32_bf16 v[92:95], v[144:147], v[184:187], v[92:95]
	v_mfma_f32_16x16x32_bf16 v[88:91], v[166:169], v[184:187], v[88:91]
	v_mfma_f32_16x16x32_bf16 v[84:87], v[144:147], v[192:195], v[84:87]
	v_mfma_f32_16x16x32_bf16 v[80:83], v[166:169], v[192:195], v[80:83]
	v_mfma_f32_16x16x32_bf16 v[76:79], v[144:147], v[200:203], v[76:79]
	v_mfma_f32_16x16x32_bf16 v[72:75], v[166:169], v[200:203], v[72:75]
	v_mfma_f32_16x16x32_bf16 v[68:71], v[144:147], v[208:211], v[68:71]
	v_mfma_f32_16x16x32_bf16 v[64:67], v[166:169], v[208:211], v[64:67]
	v_mfma_f32_16x16x32_bf16 v[92:95], v[148:151], v[188:191], v[92:95]
	v_mfma_f32_16x16x32_bf16 v[88:91], v[170:173], v[188:191], v[88:91]
	v_mfma_f32_16x16x32_bf16 v[84:87], v[148:151], v[196:199], v[84:87]
	v_mfma_f32_16x16x32_bf16 v[80:83], v[170:173], v[196:199], v[80:83]
	v_mfma_f32_16x16x32_bf16 v[76:79], v[148:151], v[204:207], v[76:79]
	v_mfma_f32_16x16x32_bf16 v[72:75], v[170:173], v[204:207], v[72:75]
	v_mfma_f32_16x16x32_bf16 v[68:71], v[148:151], v[212:215], v[68:71]
	v_mfma_f32_16x16x32_bf16 v[64:67], v[170:173], v[212:215], v[64:67]
	s_barrier
	s_add_i32 s4, s62, s28
	v_lshl_add_u64 v[174:175], v[174:175], 0, s[8:9]
	s_mov_b32 m0, s4
	ds_read_b128 v[184:187], v183 offset:49152
	ds_read_b128 v[188:191], v183 offset:50176
	ds_read_b128 v[192:195], v183 offset:51200
	ds_read_b128 v[196:199], v183 offset:52224
	ds_read_b128 v[200:203], v183 offset:53248
	ds_read_b128 v[204:207], v183 offset:54272
	ds_read_b128 v[208:211], v183 offset:55296
	ds_read_b128 v[212:215], v183 offset:56320
	global_load_lds_dwordx4 v[174:175], off
	s_add_i32 m0, s4, 0x2000
	s_add_u32 s4, s22, 0x40080
	v_lshl_add_u64 v[174:175], v[216:217], 0, s[8:9]
	s_addc_u32 s5, s23, 0
	s_add_i32 s22, s63, s28
	global_load_lds_dwordx4 v[174:175], off
	s_mov_b32 m0, s22
	s_nop 0
	global_load_lds_dwordx4 v156, s[4:5]
	s_add_i32 m0, s22, 0x2000
	s_nop 0
	global_load_lds_dwordx4 v160, s[4:5]
	v_lshl_add_u64 v[174:175], v[218:219], 0, s[8:9]
	s_mov_b32 m0, s42
	s_nop 0
	global_load_lds_dwordx4 v[174:175], off
	v_lshl_add_u64 v[174:175], v[220:221], 0, s[8:9]
	s_mov_b32 m0, s43
	s_nop 0
	global_load_lds_dwordx4 v[174:175], off
	s_waitcnt vmcnt(8) lgkmcnt(0)
	s_barrier
	v_mfma_f32_16x16x32_bf16 v[60:63], v[128:131], v[184:187], v[60:63]
	v_mfma_f32_16x16x32_bf16 v[56:59], v[136:139], v[184:187], v[56:59]
	v_mfma_f32_16x16x32_bf16 v[52:55], v[128:131], v[192:195], v[52:55]
	v_mfma_f32_16x16x32_bf16 v[48:51], v[136:139], v[192:195], v[48:51]
	v_mfma_f32_16x16x32_bf16 v[44:47], v[128:131], v[200:203], v[44:47]
	v_mfma_f32_16x16x32_bf16 v[40:43], v[136:139], v[200:203], v[40:43]
	v_mfma_f32_16x16x32_bf16 v[36:39], v[128:131], v[208:211], v[36:39]
	v_mfma_f32_16x16x32_bf16 v[32:35], v[136:139], v[208:211], v[32:35]
	v_mfma_f32_16x16x32_bf16 v[60:63], v[132:135], v[188:191], v[60:63]
	v_mfma_f32_16x16x32_bf16 v[56:59], v[140:143], v[188:191], v[56:59]
	v_mfma_f32_16x16x32_bf16 v[52:55], v[132:135], v[196:199], v[52:55]
	v_mfma_f32_16x16x32_bf16 v[48:51], v[140:143], v[196:199], v[48:51]
	v_mfma_f32_16x16x32_bf16 v[44:47], v[132:135], v[204:207], v[44:47]
	v_mfma_f32_16x16x32_bf16 v[40:43], v[140:143], v[204:207], v[40:43]
	v_mfma_f32_16x16x32_bf16 v[36:39], v[132:135], v[212:215], v[36:39]
	v_mfma_f32_16x16x32_bf16 v[32:35], v[140:143], v[212:215], v[32:35]
	v_mfma_f32_16x16x32_bf16 v[28:31], v[144:147], v[184:187], v[28:31]
	v_mfma_f32_16x16x32_bf16 v[24:27], v[166:169], v[184:187], v[24:27]
	v_mfma_f32_16x16x32_bf16 v[20:23], v[144:147], v[192:195], v[20:23]
	v_mfma_f32_16x16x32_bf16 v[16:19], v[166:169], v[192:195], v[16:19]
	v_mfma_f32_16x16x32_bf16 v[12:15], v[144:147], v[200:203], v[12:15]
	v_mfma_f32_16x16x32_bf16 v[8:11], v[166:169], v[200:203], v[8:11]
	v_mfma_f32_16x16x32_bf16 v[4:7], v[144:147], v[208:211], v[4:7]
	v_mfma_f32_16x16x32_bf16 v[0:3], v[166:169], v[208:211], v[0:3]
	v_mfma_f32_16x16x32_bf16 v[28:31], v[148:151], v[188:191], v[28:31]
	v_mfma_f32_16x16x32_bf16 v[24:27], v[170:173], v[188:191], v[24:27]
	v_mfma_f32_16x16x32_bf16 v[20:23], v[148:151], v[196:199], v[20:23]
	v_mfma_f32_16x16x32_bf16 v[16:19], v[170:173], v[196:199], v[16:19]
	v_mfma_f32_16x16x32_bf16 v[12:15], v[148:151], v[204:207], v[12:15]
	v_mfma_f32_16x16x32_bf16 v[8:11], v[170:173], v[204:207], v[8:11]
	v_mfma_f32_16x16x32_bf16 v[4:7], v[148:151], v[212:215], v[4:7]
	v_mfma_f32_16x16x32_bf16 v[0:3], v[170:173], v[212:215], v[0:3]
	s_barrier
	s_add_i32 s61, s61, 2
	s_add_u32 s53, s53, 0x100
	s_addc_u32 s60, s60, 0
	s_cmp_gt_u32 s61, 13
	s_mov_b64 s[4:5], s[20:21]
	s_cbranch_scc0 .LBB0_821
	s_setprio 0
	s_and_b64 vcc, exec, s[10:11]
	s_cbranch_vccz .LBB0_824
	s_barrier

; #define PG8_STAGE(bufoff, gbase, voff) do { _Pragma("unroll") for (int _i = 0; _i < 2; ++_i) \
;         __builtin_amdgcn_global_load_lds((const unsigned*)((const char*)(gbase) + (voff)[_i]), (LAS unsigned*)(lds + (bufoff) + ldsw + _i * 8192), 16, 0, 0); } while (0)
; #define PG8_LDA(dst, b, h) do { _Pragma("unroll") for (int m = 0; m < 4; ++m) _Pragma("unroll") for (int k = 0; k < 2; ++k) dst[m][k] = *(const LAS bf16x8*)(lds + PG8_SA(b, h) + aoff + m * 2048 + k * 1024); } while (0)
; #define PG8_LDB(dst, b, h) do { _Pragma("unroll") for (int n = 0; n < 2; ++n) _Pragma("unroll") for (int k = 0; k < 2; ++k) dst[n][k] = *(const LAS bf16x8*)(lds + PG8_SB(b, h) + boff + n * 2048 + k * 1024); } while (0)
; #define PG8_MMA(ai, bj, At, Bt) do { __builtin_amdgcn_s_setprio(1); _Pragma("unroll") for (int m = 0; m < 4; ++m) _Pragma("unroll") for (int n = 0; n < 2; ++n) _Pragma("unroll") for (int k = 0; k < 2; ++k) \
;         acc[ai][bj][m][n] = __builtin_amdgcn_mfma_f32_16x16x32_bf16(Bt[n][k], At[m][k], acc[ai][bj][m][n], 0, 0, 0); __builtin_amdgcn_s_setprio(0); } while (0)
; #define PG8_WAIT_V(n) asm volatile("s_waitcnt vmcnt(" #n ")" ::: "memory")
; #define PG8_WAIT_L(n) asm volatile("s_waitcnt lgkmcnt(" #n ")" ::: "memory")
; #define PG8_BAR __builtin_amdgcn_s_barrier()
; #define PG8_SCHED __builtin_amdgcn_sched_barrier(0)
; template <class Sched, class Epi, bool ALIGN_EPI, bool SP2>
; __device__ __forceinline__ void gemm_phase(LAS unsigned char* lds, const int K, const int lda, const int ldb, const Sched& S, const Epi& E) {
;     ...
;             PG8_LDB(B0, 0, 0); PG8_LDB(B1, 0, 1); PG8_SCHED; PG8_LDA(At, 0, 0); PG8_STAGE(PG8_SA(1, 1), a1 + hstepA, voffA);
;             PG8_WAIT_V(8); PG8_WAIT_L(0); PG8_BAR; PG8_MMA(0, 0, At, B0); PG8_MMA(0, 1, At, B1); PG8_BAR; PG8_SCHED;
;             PG8_LDA(At, 0, 1); PG8_STAGE(PG8_SB(0, 0), b2, voffB); PG8_STAGE(PG8_SB(0, 1), b2 + hstepB, voffB); PG8_STAGE(PG8_SA(0, 0), a2, voffA);
;             PG8_WAIT_V(8); PG8_WAIT_L(0); PG8_BAR; PG8_MMA(1, 0, At, B0); PG8_MMA(1, 1, At, B1); PG8_BAR; PG8_SCHED;
.Lprio_skip_945:
.LBB0_945:
	ds_read_b128 v[52:55], v209
	ds_read_b128 v[56:59], v209 offset:1024
	ds_read_b128 v[64:67], v209 offset:2048
	ds_read_b128 v[68:71], v209 offset:3072
	ds_read_b128 v[72:75], v210
	ds_read_b128 v[76:79], v210 offset:1024
	ds_read_b128 v[88:91], v210 offset:2048
	ds_read_b128 v[92:95], v210 offset:3072
	s_add_u32 s42, s36, 0xfff80080
	s_addc_u32 s43, s37, -1
	s_cmp_eq_u32 s61, 28
	s_cselect_b32 s45, s27, s43
	s_cselect_b32 s44, s26, s42
	s_cselect_b32 s43, s29, s25
	s_cselect_b32 s42, s28, s1
	s_add_i32 m0, s21, 0xc000
	ds_read_b128 v[160:163], v211
	ds_read_b128 v[164:167], v211 offset:1024
	ds_read_b128 v[168:171], v211 offset:2048
	ds_read_b128 v[172:175], v211 offset:3072
	ds_read_b128 v[190:193], v211 offset:4096
	ds_read_b128 v[194:197], v211 offset:5120
	ds_read_b128 v[198:201], v211 offset:6144
	ds_read_b128 v[202:205], v211 offset:7168
	global_load_lds_dwordx4 v186, s[36:37]
	s_add_i32 m0, s21, 0xe000
	s_nop 0
	global_load_lds_dwordx4 v188, s[36:37]
	s_waitcnt vmcnt(8) lgkmcnt(0)
	s_barrier
	v_mfma_f32_16x16x32_bf16 v[156:159], v[52:55], v[160:163], v[156:159]
	v_mfma_f32_16x16x32_bf16 v[152:155], v[64:67], v[160:163], v[152:155]
	v_mfma_f32_16x16x32_bf16 v[140:143], v[52:55], v[168:171], v[140:143]
	v_mfma_f32_16x16x32_bf16 v[136:139], v[64:67], v[168:171], v[136:139]
	v_mfma_f32_16x16x32_bf16 v[124:127], v[52:55], v[190:193], v[124:127]
	v_mfma_f32_16x16x32_bf16 v[120:123], v[64:67], v[190:193], v[120:123]
	v_mfma_f32_16x16x32_bf16 v[108:111], v[52:55], v[198:201], v[108:111]
	v_mfma_f32_16x16x32_bf16 v[104:107], v[64:67], v[198:201], v[104:107]
	v_mfma_f32_16x16x32_bf16 v[156:159], v[56:59], v[164:167], v[156:159]
	v_mfma_f32_16x16x32_bf16 v[152:155], v[68:71], v[164:167], v[152:155]
	v_mfma_f32_16x16x32_bf16 v[140:143], v[56:59], v[172:175], v[140:143]
	v_mfma_f32_16x16x32_bf16 v[136:139], v[68:71], v[172:175], v[136:139]
	v_mfma_f32_16x16x32_bf16 v[124:127], v[56:59], v[194:197], v[124:127]
	v_mfma_f32_16x16x32_bf16 v[120:123], v[68:71], v[194:197], v[120:123]
	v_mfma_f32_16x16x32_bf16 v[108:111], v[56:59], v[202:205], v[108:111]
	v_mfma_f32_16x16x32_bf16 v[104:107], v[68:71], v[202:205], v[104:107]
	v_mfma_f32_16x16x32_bf16 v[148:151], v[72:75], v[160:163], v[148:151]
	v_mfma_f32_16x16x32_bf16 v[144:147], v[88:91], v[160:163], v[144:147]
	v_mfma_f32_16x16x32_bf16 v[132:135], v[72:75], v[168:171], v[132:135]
	v_mfma_f32_16x16x32_bf16 v[128:131], v[88:91], v[168:171], v[128:131]
	v_mfma_f32_16x16x32_bf16 v[116:119], v[72:75], v[190:193], v[116:119]
	v_mfma_f32_16x16x32_bf16 v[112:115], v[88:91], v[190:193], v[112:115]
	v_mfma_f32_16x16x32_bf16 v[100:103], v[72:75], v[198:201], v[100:103]
	v_mfma_f32_16x16x32_bf16 v[96:99], v[88:91], v[198:201], v[96:99]
	v_mfma_f32_16x16x32_bf16 v[148:151], v[76:79], v[164:167], v[148:151]
	v_mfma_f32_16x16x32_bf16 v[144:147], v[92:95], v[164:167], v[144:147]
	v_mfma_f32_16x16x32_bf16 v[132:135], v[76:79], v[172:175], v[132:135]
	v_mfma_f32_16x16x32_bf16 v[128:131], v[92:95], v[172:175], v[128:131]
	v_mfma_f32_16x16x32_bf16 v[116:119], v[76:79], v[194:197], v[116:119]
	v_mfma_f32_16x16x32_bf16 v[112:115], v[92:95], v[194:197], v[112:115]
	v_mfma_f32_16x16x32_bf16 v[100:103], v[76:79], v[202:205], v[100:103]
	v_mfma_f32_16x16x32_bf16 v[96:99], v[92:95], v[202:205], v[96:99]
	s_barrier
	s_add_i32 s62, s50, s19
	v_lshl_add_u64 v[206:207], s[42:43], 0, v[182:183]
	s_mov_b32 m0, s62
	ds_read_b128 v[160:163], v211 offset:16384
	ds_read_b128 v[164:167], v211 offset:17408
	ds_read_b128 v[168:171], v211 offset:18432
	ds_read_b128 v[172:175], v211 offset:19456
	ds_read_b128 v[190:193], v211 offset:20480
	ds_read_b128 v[194:197], v211 offset:21504
	ds_read_b128 v[198:201], v211 offset:22528
	ds_read_b128 v[202:205], v211 offset:23552
	global_load_lds_dwordx4 v[206:207], off
	s_add_i32 m0, s62, 0x2000
	s_add_u32 s62, s42, 0x80000
	v_lshl_add_u64 v[214:215], s[42:43], 0, v[184:185]
	s_addc_u32 s63, s43, 0
	s_add_i32 s64, s51, s19
	global_load_lds_dwordx4 v[214:215], off
	s_mov_b32 m0, s64
	v_lshl_add_u64 v[218:219], s[44:45], 0, v[184:185]
	global_load_lds_dwordx4 v182, s[62:63]
	s_add_i32 m0, s64, 0x2000
	s_nop 0
	global_load_lds_dwordx4 v184, s[62:63]
	v_lshl_add_u64 v[216:217], s[44:45], 0, v[182:183]
	s_mov_b32 m0, s21
	s_nop 0
	global_load_lds_dwordx4 v[216:217], off
	s_mov_b32 m0, s33
	s_nop 0
	global_load_lds_dwordx4 v[218:219], off
	s_waitcnt vmcnt(8) lgkmcnt(0)
	s_barrier
	v_mfma_f32_16x16x32_bf16 v[84:87], v[52:55], v[160:163], v[84:87]
	v_mfma_f32_16x16x32_bf16 v[80:83], v[64:67], v[160:163], v[80:83]
	v_mfma_f32_16x16x32_bf16 v[44:47], v[52:55], v[168:171], v[44:47]
	v_mfma_f32_16x16x32_bf16 v[40:43], v[64:67], v[168:171], v[40:43]
	v_mfma_f32_16x16x32_bf16 v[28:31], v[52:55], v[190:193], v[28:31]
	v_mfma_f32_16x16x32_bf16 v[24:27], v[64:67], v[190:193], v[24:27]
	v_mfma_f32_16x16x32_bf16 v[12:15], v[52:55], v[198:201], v[12:15]
	v_mfma_f32_16x16x32_bf16 v[8:11], v[64:67], v[198:201], v[8:11]
	v_mfma_f32_16x16x32_bf16 v[84:87], v[56:59], v[164:167], v[84:87]
	v_mfma_f32_16x16x32_bf16 v[80:83], v[68:71], v[164:167], v[80:83]
	v_mfma_f32_16x16x32_bf16 v[44:47], v[56:59], v[172:175], v[44:47]
	v_mfma_f32_16x16x32_bf16 v[40:43], v[68:71], v[172:175], v[40:43]
	v_mfma_f32_16x16x32_bf16 v[28:31], v[56:59], v[194:197], v[28:31]
	v_mfma_f32_16x16x32_bf16 v[24:27], v[68:71], v[194:197], v[24:27]
	v_mfma_f32_16x16x32_bf16 v[12:15], v[56:59], v[202:205], v[12:15]
	v_mfma_f32_16x16x32_bf16 v[8:11], v[68:71], v[202:205], v[8:11]
	v_mfma_f32_16x16x32_bf16 v[48:51], v[88:91], v[160:163], v[48:51]
	v_mfma_f32_16x16x32_bf16 v[36:39], v[72:75], v[168:171], v[36:39]
	v_mfma_f32_16x16x32_bf16 v[32:35], v[88:91], v[168:171], v[32:35]
	v_mfma_f32_16x16x32_bf16 v[20:23], v[72:75], v[190:193], v[20:23]
	v_mfma_f32_16x16x32_bf16 v[16:19], v[88:91], v[190:193], v[16:19]
	v_mfma_f32_16x16x32_bf16 v[4:7], v[72:75], v[198:201], v[4:7]
	v_mfma_f32_16x16x32_bf16 v[0:3], v[88:91], v[198:201], v[0:3]
	v_mfma_f32_16x16x32_bf16 v[52:55], v[72:75], v[160:163], v[60:63]
	v_mfma_f32_16x16x32_bf16 v[48:51], v[92:95], v[164:167], v[48:51]
	v_mfma_f32_16x16x32_bf16 v[36:39], v[76:79], v[172:175], v[36:39]
	v_mfma_f32_16x16x32_bf16 v[32:35], v[92:95], v[172:175], v[32:35]
	v_mfma_f32_16x16x32_bf16 v[20:23], v[76:79], v[194:197], v[20:23]
	v_mfma_f32_16x16x32_bf16 v[16:19], v[92:95], v[194:197], v[16:19]
	v_mfma_f32_16x16x32_bf16 v[4:7], v[76:79], v[202:205], v[4:7]
	v_mfma_f32_16x16x32_bf16 v[0:3], v[92:95], v[202:205], v[0:3]
	v_mfma_f32_16x16x32_bf16 v[52:55], v[76:79], v[164:167], v[52:55]
	s_barrier
; #define PG8_STAGE(bufoff, gbase, voff) do { _Pragma("unroll") for (int _i = 0; _i < 2; ++_i) \
;         __builtin_amdgcn_global_load_lds((const unsigned*)((const char*)(gbase) + (voff)[_i]), (LAS unsigned*)(lds + (bufoff) + ldsw + _i * 8192), 16, 0, 0); } while (0)
; #define PG8_LDA(dst, b, h) do { _Pragma("unroll") for (int m = 0; m < 4; ++m) _Pragma("unroll") for (int k = 0; k < 2; ++k) dst[m][k] = *(const LAS bf16x8*)(lds + PG8_SA(b, h) + aoff + m * 2048 + k * 1024); } while (0)
; #define PG8_LDB(dst, b, h) do { _Pragma("unroll") for (int n = 0; n < 2; ++n) _Pragma("unroll") for (int k = 0; k < 2; ++k) dst[n][k] = *(const LAS bf16x8*)(lds + PG8_SB(b, h) + boff + n * 2048 + k * 1024); } while (0)
; #define PG8_MMA(ai, bj, At, Bt) do { __builtin_amdgcn_s_setprio(1); _Pragma("unroll") for (int m = 0; m < 4; ++m) _Pragma("unroll") for (int n = 0; n < 2; ++n) _Pragma("unroll") for (int k = 0; k < 2; ++k) \
;         acc[ai][bj][m][n] = __builtin_amdgcn_mfma_f32_16x16x32_bf16(Bt[n][k], At[m][k], acc[ai][bj][m][n], 0, 0, 0); __builtin_amdgcn_s_setprio(0); } while (0)
; #define PG8_WAIT_V(n) asm volatile("s_waitcnt vmcnt(" #n ")" ::: "memory")
; #define PG8_WAIT_L(n) asm volatile("s_waitcnt lgkmcnt(" #n ")" ::: "memory")
; #define PG8_BAR __builtin_amdgcn_s_barrier()
; #define PG8_SCHED __builtin_amdgcn_sched_barrier(0)
; template <class Sched, class Epi, bool ALIGN_EPI, bool SP2>
; __device__ __forceinline__ void gemm_phase(LAS unsigned char* lds, const int K, const int lda, const int ldb, const Sched& S, const Epi& E) {
;     ...
;             PG8_LDB(B0, 1, 0); PG8_LDB(B1, 1, 1); PG8_SCHED; PG8_LDA(At, 1, 0); PG8_STAGE(PG8_SA(0, 1), a2 + hstepA, voffA);
;             PG8_WAIT_V(8); PG8_WAIT_L(0); PG8_BAR; PG8_MMA(0, 0, At, B0); PG8_MMA(0, 1, At, B1); PG8_BAR; PG8_SCHED;
;             PG8_LDA(At, 1, 1); PG8_STAGE(PG8_SB(1, 0), b3, voffB); PG8_STAGE(PG8_SB(1, 1), b3 + hstepB, voffB); PG8_STAGE(PG8_SA(1, 0), a3, voffA);
;             PG8_WAIT_V(8); PG8_WAIT_L(0); PG8_BAR; PG8_MMA(1, 0, At, B0); PG8_MMA(1, 1, At, B1); PG8_BAR; PG8_SCHED;
	s_add_i32 s62, 0, 0x18000
	s_add_i32 s63, 0, 0x1c000
	v_add_u32_e32 v68, s62, v181
	v_add_u32_e32 v92, s63, v181
	ds_read_b128 v[56:59], v68
	ds_read_b128 v[60:63], v68 offset:1024
	ds_read_b128 v[64:67], v68 offset:2048
	ds_read_b128 v[68:71], v68 offset:3072
	ds_read_b128 v[72:75], v92
	ds_read_b128 v[76:79], v92 offset:1024
	ds_read_b128 v[88:91], v92 offset:2048
	ds_read_b128 v[92:95], v92 offset:3072
	s_add_u32 s44, s44, 0x80000
	s_addc_u32 s45, s45, 0
	s_mov_b32 m0, s35
	ds_read_b128 v[160:163], v211 offset:32768
	ds_read_b128 v[164:167], v211 offset:33792
	ds_read_b128 v[168:171], v211 offset:34816
	ds_read_b128 v[172:175], v211 offset:35840
	ds_read_b128 v[190:193], v211 offset:36864
	ds_read_b128 v[194:197], v211 offset:37888
	ds_read_b128 v[198:201], v211 offset:38912
	ds_read_b128 v[202:205], v211 offset:39936
	global_load_lds_dwordx4 v182, s[44:45]
	s_mov_b32 m0, s46
	s_nop 0
	global_load_lds_dwordx4 v184, s[44:45]
	s_waitcnt vmcnt(8) lgkmcnt(0)
	s_barrier
	v_mfma_f32_16x16x32_bf16 v[156:159], v[56:59], v[160:163], v[156:159]
	v_mfma_f32_16x16x32_bf16 v[152:155], v[64:67], v[160:163], v[152:155]
	v_mfma_f32_16x16x32_bf16 v[140:143], v[56:59], v[168:171], v[140:143]
	v_mfma_f32_16x16x32_bf16 v[136:139], v[64:67], v[168:171], v[136:139]
	v_mfma_f32_16x16x32_bf16 v[124:127], v[56:59], v[190:193], v[124:127]
	v_mfma_f32_16x16x32_bf16 v[120:123], v[64:67], v[190:193], v[120:123]
	v_mfma_f32_16x16x32_bf16 v[108:111], v[56:59], v[198:201], v[108:111]
	v_mfma_f32_16x16x32_bf16 v[104:107], v[64:67], v[198:201], v[104:107]
	v_mfma_f32_16x16x32_bf16 v[156:159], v[60:63], v[164:167], v[156:159]
	v_mfma_f32_16x16x32_bf16 v[152:155], v[68:71], v[164:167], v[152:155]
	v_mfma_f32_16x16x32_bf16 v[140:143], v[60:63], v[172:175], v[140:143]
	v_mfma_f32_16x16x32_bf16 v[136:139], v[68:71], v[172:175], v[136:139]
	v_mfma_f32_16x16x32_bf16 v[124:127], v[60:63], v[194:197], v[124:127]
	v_mfma_f32_16x16x32_bf16 v[120:123], v[68:71], v[194:197], v[120:123]
	v_mfma_f32_16x16x32_bf16 v[108:111], v[60:63], v[202:205], v[108:111]
	v_mfma_f32_16x16x32_bf16 v[104:107], v[68:71], v[202:205], v[104:107]
	v_mfma_f32_16x16x32_bf16 v[148:151], v[72:75], v[160:163], v[148:151]
	v_mfma_f32_16x16x32_bf16 v[144:147], v[88:91], v[160:163], v[144:147]
	v_mfma_f32_16x16x32_bf16 v[132:135], v[72:75], v[168:171], v[132:135]
	v_mfma_f32_16x16x32_bf16 v[128:131], v[88:91], v[168:171], v[128:131]
	v_mfma_f32_16x16x32_bf16 v[116:119], v[72:75], v[190:193], v[116:119]
	v_mfma_f32_16x16x32_bf16 v[112:115], v[88:91], v[190:193], v[112:115]
	v_mfma_f32_16x16x32_bf16 v[100:103], v[72:75], v[198:201], v[100:103]
	v_mfma_f32_16x16x32_bf16 v[96:99], v[88:91], v[198:201], v[96:99]
	v_mfma_f32_16x16x32_bf16 v[148:151], v[76:79], v[164:167], v[148:151]
	v_mfma_f32_16x16x32_bf16 v[144:147], v[92:95], v[164:167], v[144:147]
	v_mfma_f32_16x16x32_bf16 v[132:135], v[76:79], v[172:175], v[132:135]
	v_mfma_f32_16x16x32_bf16 v[128:131], v[92:95], v[172:175], v[128:131]
	v_mfma_f32_16x16x32_bf16 v[116:119], v[76:79], v[194:197], v[116:119]
	v_mfma_f32_16x16x32_bf16 v[112:115], v[92:95], v[194:197], v[112:115]
	v_mfma_f32_16x16x32_bf16 v[100:103], v[76:79], v[202:205], v[100:103]
	v_mfma_f32_16x16x32_bf16 v[96:99], v[92:95], v[202:205], v[96:99]
	s_barrier
	s_add_i32 s44, s62, s19
	v_lshl_add_u64 v[206:207], v[206:207], 0, s[14:15]
	s_mov_b32 m0, s44
	ds_read_b128 v[160:163], v211 offset:49152
	ds_read_b128 v[164:167], v211 offset:50176
	ds_read_b128 v[168:171], v211 offset:51200
	ds_read_b128 v[172:175], v211 offset:52224
	ds_read_b128 v[190:193], v211 offset:53248
	ds_read_b128 v[194:197], v211 offset:54272
	ds_read_b128 v[198:201], v211 offset:55296
	ds_read_b128 v[202:205], v211 offset:56320
	global_load_lds_dwordx4 v[206:207], off
	s_add_i32 m0, s44, 0x2000
	s_add_u32 s42, s42, 0x80080
	v_lshl_add_u64 v[206:207], v[214:215], 0, s[14:15]
	s_addc_u32 s43, s43, 0
	s_add_i32 s44, s63, s19
	global_load_lds_dwordx4 v[206:207], off
	s_mov_b32 m0, s44
	s_nop 0
	global_load_lds_dwordx4 v182, s[42:43]
	s_add_i32 m0, s44, 0x2000
	s_nop 0
	global_load_lds_dwordx4 v184, s[42:43]
	v_lshl_add_u64 v[206:207], v[216:217], 0, s[14:15]
	s_mov_b32 m0, s48
	s_nop 0
	global_load_lds_dwordx4 v[206:207], off
	v_lshl_add_u64 v[206:207], v[218:219], 0, s[14:15]
	s_mov_b32 m0, s49
	s_nop 0
	global_load_lds_dwordx4 v[206:207], off
	s_waitcnt vmcnt(8) lgkmcnt(0)
	s_barrier
	v_mfma_f32_16x16x32_bf16 v[84:87], v[56:59], v[160:163], v[84:87]
	v_mfma_f32_16x16x32_bf16 v[80:83], v[64:67], v[160:163], v[80:83]
	v_mfma_f32_16x16x32_bf16 v[44:47], v[56:59], v[168:171], v[44:47]
	v_mfma_f32_16x16x32_bf16 v[40:43], v[64:67], v[168:171], v[40:43]
	v_mfma_f32_16x16x32_bf16 v[28:31], v[56:59], v[190:193], v[28:31]
	v_mfma_f32_16x16x32_bf16 v[24:27], v[64:67], v[190:193], v[24:27]
	v_mfma_f32_16x16x32_bf16 v[12:15], v[56:59], v[198:201], v[12:15]
	v_mfma_f32_16x16x32_bf16 v[8:11], v[64:67], v[198:201], v[8:11]
	v_mfma_f32_16x16x32_bf16 v[84:87], v[60:63], v[164:167], v[84:87]
	v_mfma_f32_16x16x32_bf16 v[80:83], v[68:71], v[164:167], v[80:83]
	v_mfma_f32_16x16x32_bf16 v[44:47], v[60:63], v[172:175], v[44:47]
	v_mfma_f32_16x16x32_bf16 v[40:43], v[68:71], v[172:175], v[40:43]
	v_mfma_f32_16x16x32_bf16 v[28:31], v[60:63], v[194:197], v[28:31]
	v_mfma_f32_16x16x32_bf16 v[24:27], v[68:71], v[194:197], v[24:27]
	v_mfma_f32_16x16x32_bf16 v[12:15], v[60:63], v[202:205], v[12:15]
	v_mfma_f32_16x16x32_bf16 v[8:11], v[68:71], v[202:205], v[8:11]
	v_mfma_f32_16x16x32_bf16 v[52:55], v[72:75], v[160:163], v[52:55]
	v_mfma_f32_16x16x32_bf16 v[48:51], v[88:91], v[160:163], v[48:51]
	v_mfma_f32_16x16x32_bf16 v[36:39], v[72:75], v[168:171], v[36:39]
	v_mfma_f32_16x16x32_bf16 v[32:35], v[88:91], v[168:171], v[32:35]
	v_mfma_f32_16x16x32_bf16 v[20:23], v[72:75], v[190:193], v[20:23]
	v_mfma_f32_16x16x32_bf16 v[16:19], v[88:91], v[190:193], v[16:19]
	v_mfma_f32_16x16x32_bf16 v[4:7], v[72:75], v[198:201], v[4:7]
	v_mfma_f32_16x16x32_bf16 v[0:3], v[88:91], v[198:201], v[0:3]
	v_mfma_f32_16x16x32_bf16 v[60:63], v[76:79], v[164:167], v[52:55]
	v_mfma_f32_16x16x32_bf16 v[48:51], v[92:95], v[164:167], v[48:51]
	v_mfma_f32_16x16x32_bf16 v[36:39], v[76:79], v[172:175], v[36:39]
	v_mfma_f32_16x16x32_bf16 v[32:35], v[92:95], v[172:175], v[32:35]
	v_mfma_f32_16x16x32_bf16 v[20:23], v[76:79], v[194:197], v[20:23]
	v_mfma_f32_16x16x32_bf16 v[16:19], v[92:95], v[194:197], v[16:19]
	v_mfma_f32_16x16x32_bf16 v[4:7], v[76:79], v[202:205], v[4:7]
	v_mfma_f32_16x16x32_bf16 v[0:3], v[92:95], v[202:205], v[0:3]
	s_barrier
	s_add_i32 s61, s61, 2
	s_add_u32 s36, s36, 0x100
	s_addc_u32 s37, s37, 0
	s_add_u32 s1, s1, 0x100
	s_addc_u32 s25, s25, 0
	s_cmp_gt_u32 s61, 29
	s_cbranch_scc0 .LBB0_945
	s_setprio 0
	s_and_b64 vcc, exec, s[16:17]
	s_cbranch_vccz .LBB0_948
	s_barrier

; #define PG8_STAGE(bufoff, gbase, voff) do { _Pragma("unroll") for (int _i = 0; _i < 2; ++_i) \
;         __builtin_amdgcn_global_load_lds((const unsigned*)((const char*)(gbase) + (voff)[_i]), (LAS unsigned*)(lds + (bufoff) + ldsw + _i * 8192), 16, 0, 0); } while (0)
; #define PG8_LDA(dst, b, h) do { _Pragma("unroll") for (int m = 0; m < 4; ++m) _Pragma("unroll") for (int k = 0; k < 2; ++k) dst[m][k] = *(const LAS bf16x8*)(lds + PG8_SA(b, h) + aoff + m * 2048 + k * 1024); } while (0)
; #define PG8_LDB(dst, b, h) do { _Pragma("unroll") for (int n = 0; n < 2; ++n) _Pragma("unroll") for (int k = 0; k < 2; ++k) dst[n][k] = *(const LAS bf16x8*)(lds + PG8_SB(b, h) + boff + n * 2048 + k * 1024); } while (0)
; #define PG8_MMA(ai, bj, At, Bt) do { __builtin_amdgcn_s_setprio(1); _Pragma("unroll") for (int m = 0; m < 4; ++m) _Pragma("unroll") for (int n = 0; n < 2; ++n) _Pragma("unroll") for (int k = 0; k < 2; ++k) \
;         acc[ai][bj][m][n] = __builtin_amdgcn_mfma_f32_16x16x32_bf16(Bt[n][k], At[m][k], acc[ai][bj][m][n], 0, 0, 0); __builtin_amdgcn_s_setprio(0); } while (0)
; #define PG8_WAIT_V(n) asm volatile("s_waitcnt vmcnt(" #n ")" ::: "memory")
; #define PG8_WAIT_L(n) asm volatile("s_waitcnt lgkmcnt(" #n ")" ::: "memory")
; #define PG8_BAR __builtin_amdgcn_s_barrier()
; #define PG8_SCHED __builtin_amdgcn_sched_barrier(0)
; template <class Sched, class Epi, bool ALIGN_EPI, bool SP2>
; __device__ __forceinline__ void gemm_phase(LAS unsigned char* lds, const int K, const int lda, const int ldb, const Sched& S, const Epi& E) {
;     ...
;             PG8_LDB(B0, 0, 0); PG8_LDB(B1, 0, 1); PG8_SCHED; PG8_LDA(At, 0, 0); PG8_STAGE(PG8_SA(1, 1), a1 + hstepA, voffA);
;             PG8_WAIT_V(8); PG8_WAIT_L(0); PG8_BAR; PG8_MMA(0, 0, At, B0); PG8_MMA(0, 1, At, B1); PG8_BAR; PG8_SCHED;
;             PG8_LDA(At, 0, 1); PG8_STAGE(PG8_SB(0, 0), b2, voffB); PG8_STAGE(PG8_SB(0, 1), b2 + hstepB, voffB); PG8_STAGE(PG8_SA(0, 0), a2, voffA);
;             PG8_WAIT_V(8); PG8_WAIT_L(0); PG8_BAR; PG8_MMA(1, 0, At, B0); PG8_MMA(1, 1, At, B1); PG8_BAR; PG8_SCHED;
.Lprio_skip_1037:
.LBB0_1037:
	ds_read_b128 v[64:67], v183
	ds_read_b128 v[68:71], v183 offset:1024
	ds_read_b128 v[72:75], v183 offset:2048
	ds_read_b128 v[76:79], v183 offset:3072
	ds_read_b128 v[144:147], v184
	ds_read_b128 v[160:163], v184 offset:1024
	ds_read_b128 v[164:167], v184 offset:2048
	ds_read_b128 v[168:171], v184 offset:3072
	s_add_u32 s42, s36, 0xfff80080
	s_addc_u32 s43, s37, -1
	s_cmp_eq_u32 s57, 28
	s_cselect_b32 s45, s27, s43
	s_cselect_b32 s44, s26, s42
	s_cselect_b32 s43, s29, s56
	s_cselect_b32 s42, s28, s25
	s_add_i32 m0, s33, 0xc000
	ds_read_b128 v[172:175], v185
	ds_read_b128 v[188:191], v185 offset:1024
	ds_read_b128 v[192:195], v185 offset:2048
	ds_read_b128 v[196:199], v185 offset:3072
	ds_read_b128 v[200:203], v185 offset:4096
	ds_read_b128 v[204:207], v185 offset:5120
	ds_read_b128 v[208:211], v185 offset:6144
	ds_read_b128 v[212:215], v185 offset:7168
	global_load_lds_dwordx4 v156, s[36:37]
	s_add_i32 m0, s33, 0xe000
	s_nop 0
	global_load_lds_dwordx4 v158, s[36:37]
	s_waitcnt vmcnt(8) lgkmcnt(0)
	s_barrier
	v_mfma_f32_16x16x32_bf16 v[140:143], v[64:67], v[172:175], v[140:143]
	v_mfma_f32_16x16x32_bf16 v[136:139], v[72:75], v[172:175], v[136:139]
	v_mfma_f32_16x16x32_bf16 v[124:127], v[64:67], v[192:195], v[124:127]
	v_mfma_f32_16x16x32_bf16 v[120:123], v[72:75], v[192:195], v[120:123]
	v_mfma_f32_16x16x32_bf16 v[108:111], v[64:67], v[200:203], v[108:111]
	v_mfma_f32_16x16x32_bf16 v[104:107], v[72:75], v[200:203], v[104:107]
	v_mfma_f32_16x16x32_bf16 v[92:95], v[64:67], v[208:211], v[92:95]
	v_mfma_f32_16x16x32_bf16 v[88:91], v[72:75], v[208:211], v[88:91]
	v_mfma_f32_16x16x32_bf16 v[140:143], v[68:71], v[188:191], v[140:143]
	v_mfma_f32_16x16x32_bf16 v[136:139], v[76:79], v[188:191], v[136:139]
	v_mfma_f32_16x16x32_bf16 v[124:127], v[68:71], v[196:199], v[124:127]
	v_mfma_f32_16x16x32_bf16 v[120:123], v[76:79], v[196:199], v[120:123]
	v_mfma_f32_16x16x32_bf16 v[108:111], v[68:71], v[204:207], v[108:111]
	v_mfma_f32_16x16x32_bf16 v[104:107], v[76:79], v[204:207], v[104:107]
	v_mfma_f32_16x16x32_bf16 v[92:95], v[68:71], v[212:215], v[92:95]
	v_mfma_f32_16x16x32_bf16 v[88:91], v[76:79], v[212:215], v[88:91]
	v_mfma_f32_16x16x32_bf16 v[132:135], v[144:147], v[172:175], v[132:135]
	v_mfma_f32_16x16x32_bf16 v[128:131], v[164:167], v[172:175], v[128:131]
	v_mfma_f32_16x16x32_bf16 v[116:119], v[144:147], v[192:195], v[116:119]
	v_mfma_f32_16x16x32_bf16 v[112:115], v[164:167], v[192:195], v[112:115]
	v_mfma_f32_16x16x32_bf16 v[100:103], v[144:147], v[200:203], v[100:103]
	v_mfma_f32_16x16x32_bf16 v[96:99], v[164:167], v[200:203], v[96:99]
	v_mfma_f32_16x16x32_bf16 v[84:87], v[144:147], v[208:211], v[84:87]
	v_mfma_f32_16x16x32_bf16 v[80:83], v[164:167], v[208:211], v[80:83]
	v_mfma_f32_16x16x32_bf16 v[132:135], v[160:163], v[188:191], v[132:135]
	v_mfma_f32_16x16x32_bf16 v[128:131], v[168:171], v[188:191], v[128:131]
	v_mfma_f32_16x16x32_bf16 v[116:119], v[160:163], v[196:199], v[116:119]
	v_mfma_f32_16x16x32_bf16 v[112:115], v[168:171], v[196:199], v[112:115]
	v_mfma_f32_16x16x32_bf16 v[100:103], v[160:163], v[204:207], v[100:103]
	v_mfma_f32_16x16x32_bf16 v[96:99], v[168:171], v[204:207], v[96:99]
	v_mfma_f32_16x16x32_bf16 v[84:87], v[160:163], v[212:215], v[84:87]
	v_mfma_f32_16x16x32_bf16 v[80:83], v[168:171], v[212:215], v[80:83]
	s_barrier
	s_add_i32 s58, s51, s21
	v_lshl_add_u64 v[216:217], s[42:43], 0, v[150:151]
	s_mov_b32 m0, s58
	ds_read_b128 v[172:175], v185 offset:16384
	ds_read_b128 v[188:191], v185 offset:17408
	ds_read_b128 v[192:195], v185 offset:18432
	ds_read_b128 v[196:199], v185 offset:19456
	ds_read_b128 v[200:203], v185 offset:20480
	ds_read_b128 v[204:207], v185 offset:21504
	ds_read_b128 v[208:211], v185 offset:22528
	ds_read_b128 v[212:215], v185 offset:23552
	global_load_lds_dwordx4 v[216:217], off
	s_add_i32 m0, s58, 0x2000
	s_add_u32 s58, s42, 0x80000
	v_lshl_add_u64 v[218:219], s[42:43], 0, v[154:155]
	s_addc_u32 s59, s43, 0
	s_add_i32 s60, s52, s21
	global_load_lds_dwordx4 v[218:219], off
	s_mov_b32 m0, s60
	v_lshl_add_u64 v[222:223], s[44:45], 0, v[152:153]
	global_load_lds_dwordx4 v150, s[58:59]
	s_add_i32 m0, s60, 0x2000
	s_nop 0
	global_load_lds_dwordx4 v154, s[58:59]
	v_lshl_add_u64 v[220:221], s[44:45], 0, v[148:149]
	s_mov_b32 m0, s33
	s_nop 0
	global_load_lds_dwordx4 v[220:221], off
	s_mov_b32 m0, s35
	s_nop 0
	global_load_lds_dwordx4 v[222:223], off
	s_waitcnt vmcnt(8) lgkmcnt(0)
	s_barrier
	v_mfma_f32_16x16x32_bf16 v[60:63], v[64:67], v[172:175], v[60:63]
	v_mfma_f32_16x16x32_bf16 v[56:59], v[72:75], v[172:175], v[56:59]
	v_mfma_f32_16x16x32_bf16 v[44:47], v[64:67], v[192:195], v[44:47]
	v_mfma_f32_16x16x32_bf16 v[40:43], v[72:75], v[192:195], v[40:43]
	v_mfma_f32_16x16x32_bf16 v[24:27], v[64:67], v[200:203], v[24:27]
	v_mfma_f32_16x16x32_bf16 v[20:23], v[72:75], v[200:203], v[20:23]
	v_mfma_f32_16x16x32_bf16 v[8:11], v[64:67], v[208:211], v[8:11]
	v_mfma_f32_16x16x32_bf16 v[0:3], v[72:75], v[208:211], v[0:3]
	v_mfma_f32_16x16x32_bf16 v[60:63], v[68:71], v[188:191], v[60:63]
	v_mfma_f32_16x16x32_bf16 v[56:59], v[76:79], v[188:191], v[56:59]
	v_mfma_f32_16x16x32_bf16 v[44:47], v[68:71], v[196:199], v[44:47]
	v_mfma_f32_16x16x32_bf16 v[40:43], v[76:79], v[196:199], v[40:43]
	v_mfma_f32_16x16x32_bf16 v[24:27], v[68:71], v[204:207], v[24:27]
	v_mfma_f32_16x16x32_bf16 v[20:23], v[76:79], v[204:207], v[20:23]
	v_mfma_f32_16x16x32_bf16 v[8:11], v[68:71], v[212:215], v[8:11]
	v_mfma_f32_16x16x32_bf16 v[0:3], v[76:79], v[212:215], v[0:3]
	v_mfma_f32_16x16x32_bf16 v[52:55], v[144:147], v[172:175], v[52:55]
	v_mfma_f32_16x16x32_bf16 v[48:51], v[164:167], v[172:175], v[48:51]
	v_mfma_f32_16x16x32_bf16 v[36:39], v[144:147], v[192:195], v[36:39]
	v_mfma_f32_16x16x32_bf16 v[32:35], v[164:167], v[192:195], v[32:35]
	v_mfma_f32_16x16x32_bf16 v[28:31], v[144:147], v[200:203], v[28:31]
	v_mfma_f32_16x16x32_bf16 v[16:19], v[164:167], v[200:203], v[16:19]
	v_mfma_f32_16x16x32_bf16 v[12:15], v[144:147], v[208:211], v[12:15]
	v_mfma_f32_16x16x32_bf16 v[4:7], v[164:167], v[208:211], v[4:7]
	v_mfma_f32_16x16x32_bf16 v[52:55], v[160:163], v[188:191], v[52:55]
	v_mfma_f32_16x16x32_bf16 v[48:51], v[168:171], v[188:191], v[48:51]
	v_mfma_f32_16x16x32_bf16 v[36:39], v[160:163], v[196:199], v[36:39]
	v_mfma_f32_16x16x32_bf16 v[32:35], v[168:171], v[196:199], v[32:35]
	v_mfma_f32_16x16x32_bf16 v[28:31], v[160:163], v[204:207], v[28:31]
	v_mfma_f32_16x16x32_bf16 v[16:19], v[168:171], v[204:207], v[16:19]
	v_mfma_f32_16x16x32_bf16 v[12:15], v[160:163], v[212:215], v[12:15]
	v_mfma_f32_16x16x32_bf16 v[4:7], v[168:171], v[212:215], v[4:7]
	s_barrier
; #define PG8_STAGE(bufoff, gbase, voff) do { _Pragma("unroll") for (int _i = 0; _i < 2; ++_i) \
;         __builtin_amdgcn_global_load_lds((const unsigned*)((const char*)(gbase) + (voff)[_i]), (LAS unsigned*)(lds + (bufoff) + ldsw + _i * 8192), 16, 0, 0); } while (0)
; #define PG8_LDA(dst, b, h) do { _Pragma("unroll") for (int m = 0; m < 4; ++m) _Pragma("unroll") for (int k = 0; k < 2; ++k) dst[m][k] = *(const LAS bf16x8*)(lds + PG8_SA(b, h) + aoff + m * 2048 + k * 1024); } while (0)
; #define PG8_LDB(dst, b, h) do { _Pragma("unroll") for (int n = 0; n < 2; ++n) _Pragma("unroll") for (int k = 0; k < 2; ++k) dst[n][k] = *(const LAS bf16x8*)(lds + PG8_SB(b, h) + boff + n * 2048 + k * 1024); } while (0)
; #define PG8_MMA(ai, bj, At, Bt) do { __builtin_amdgcn_s_setprio(1); _Pragma("unroll") for (int m = 0; m < 4; ++m) _Pragma("unroll") for (int n = 0; n < 2; ++n) _Pragma("unroll") for (int k = 0; k < 2; ++k) \
;         acc[ai][bj][m][n] = __builtin_amdgcn_mfma_f32_16x16x32_bf16(Bt[n][k], At[m][k], acc[ai][bj][m][n], 0, 0, 0); __builtin_amdgcn_s_setprio(0); } while (0)
; #define PG8_WAIT_V(n) asm volatile("s_waitcnt vmcnt(" #n ")" ::: "memory")
; #define PG8_WAIT_L(n) asm volatile("s_waitcnt lgkmcnt(" #n ")" ::: "memory")
; #define PG8_BAR __builtin_amdgcn_s_barrier()
; #define PG8_SCHED __builtin_amdgcn_sched_barrier(0)
; template <class Sched, class Epi, bool ALIGN_EPI, bool SP2>
; __device__ __forceinline__ void gemm_phase(LAS unsigned char* lds, const int K, const int lda, const int ldb, const Sched& S, const Epi& E) {
;     ...
;             PG8_LDB(B0, 1, 0); PG8_LDB(B1, 1, 1); PG8_SCHED; PG8_LDA(At, 1, 0); PG8_STAGE(PG8_SA(0, 1), a2 + hstepA, voffA);
;             PG8_WAIT_V(8); PG8_WAIT_L(0); PG8_BAR; PG8_MMA(0, 0, At, B0); PG8_MMA(0, 1, At, B1); PG8_BAR; PG8_SCHED;
;             PG8_LDA(At, 1, 1); PG8_STAGE(PG8_SB(1, 0), b3, voffB); PG8_STAGE(PG8_SB(1, 1), b3 + hstepB, voffB); PG8_STAGE(PG8_SA(1, 0), a3, voffA);
;             PG8_WAIT_V(8); PG8_WAIT_L(0); PG8_BAR; PG8_MMA(1, 0, At, B0); PG8_MMA(1, 1, At, B1); PG8_BAR; PG8_SCHED;
	s_add_i32 s58, 0, 0x18000
	s_add_i32 s59, 0, 0x1c000
	v_add_u32_e32 v76, s58, v181
	v_add_u32_e32 v168, s59, v181
	ds_read_b128 v[64:67], v76
	ds_read_b128 v[68:71], v76 offset:1024
	ds_read_b128 v[72:75], v76 offset:2048
	ds_read_b128 v[76:79], v76 offset:3072
	ds_read_b128 v[144:147], v168
	ds_read_b128 v[160:163], v168 offset:1024
	ds_read_b128 v[164:167], v168 offset:2048
	ds_read_b128 v[168:171], v168 offset:3072
	s_add_u32 s44, s44, 0x80000
	s_addc_u32 s45, s45, 0
	s_mov_b32 m0, s46
	ds_read_b128 v[172:175], v185 offset:32768
	ds_read_b128 v[188:191], v185 offset:33792
	ds_read_b128 v[192:195], v185 offset:34816
	ds_read_b128 v[196:199], v185 offset:35840
	ds_read_b128 v[200:203], v185 offset:36864
	ds_read_b128 v[204:207], v185 offset:37888
	ds_read_b128 v[208:211], v185 offset:38912
	ds_read_b128 v[212:215], v185 offset:39936
	global_load_lds_dwordx4 v148, s[44:45]
	s_mov_b32 m0, s47
	s_nop 0
	global_load_lds_dwordx4 v152, s[44:45]
	s_waitcnt vmcnt(8) lgkmcnt(0)
	s_barrier
	v_mfma_f32_16x16x32_bf16 v[140:143], v[64:67], v[172:175], v[140:143]
	v_mfma_f32_16x16x32_bf16 v[136:139], v[72:75], v[172:175], v[136:139]
	v_mfma_f32_16x16x32_bf16 v[124:127], v[64:67], v[192:195], v[124:127]
	v_mfma_f32_16x16x32_bf16 v[120:123], v[72:75], v[192:195], v[120:123]
	v_mfma_f32_16x16x32_bf16 v[108:111], v[64:67], v[200:203], v[108:111]
	v_mfma_f32_16x16x32_bf16 v[104:107], v[72:75], v[200:203], v[104:107]
	v_mfma_f32_16x16x32_bf16 v[92:95], v[64:67], v[208:211], v[92:95]
	v_mfma_f32_16x16x32_bf16 v[88:91], v[72:75], v[208:211], v[88:91]
	v_mfma_f32_16x16x32_bf16 v[140:143], v[68:71], v[188:191], v[140:143]
	v_mfma_f32_16x16x32_bf16 v[136:139], v[76:79], v[188:191], v[136:139]
	v_mfma_f32_16x16x32_bf16 v[124:127], v[68:71], v[196:199], v[124:127]
	v_mfma_f32_16x16x32_bf16 v[120:123], v[76:79], v[196:199], v[120:123]
	v_mfma_f32_16x16x32_bf16 v[108:111], v[68:71], v[204:207], v[108:111]
	v_mfma_f32_16x16x32_bf16 v[104:107], v[76:79], v[204:207], v[104:107]
	v_mfma_f32_16x16x32_bf16 v[92:95], v[68:71], v[212:215], v[92:95]
	v_mfma_f32_16x16x32_bf16 v[88:91], v[76:79], v[212:215], v[88:91]
	v_mfma_f32_16x16x32_bf16 v[132:135], v[144:147], v[172:175], v[132:135]
	v_mfma_f32_16x16x32_bf16 v[128:131], v[164:167], v[172:175], v[128:131]
	v_mfma_f32_16x16x32_bf16 v[116:119], v[144:147], v[192:195], v[116:119]
	v_mfma_f32_16x16x32_bf16 v[112:115], v[164:167], v[192:195], v[112:115]
	v_mfma_f32_16x16x32_bf16 v[100:103], v[144:147], v[200:203], v[100:103]
	v_mfma_f32_16x16x32_bf16 v[96:99], v[164:167], v[200:203], v[96:99]
	v_mfma_f32_16x16x32_bf16 v[84:87], v[144:147], v[208:211], v[84:87]
	v_mfma_f32_16x16x32_bf16 v[80:83], v[164:167], v[208:211], v[80:83]
	v_mfma_f32_16x16x32_bf16 v[132:135], v[160:163], v[188:191], v[132:135]
	v_mfma_f32_16x16x32_bf16 v[128:131], v[168:171], v[188:191], v[128:131]
	v_mfma_f32_16x16x32_bf16 v[116:119], v[160:163], v[196:199], v[116:119]
	v_mfma_f32_16x16x32_bf16 v[112:115], v[168:171], v[196:199], v[112:115]
	v_mfma_f32_16x16x32_bf16 v[100:103], v[160:163], v[204:207], v[100:103]
	v_mfma_f32_16x16x32_bf16 v[96:99], v[168:171], v[204:207], v[96:99]
	v_mfma_f32_16x16x32_bf16 v[84:87], v[160:163], v[212:215], v[84:87]
	v_mfma_f32_16x16x32_bf16 v[80:83], v[168:171], v[212:215], v[80:83]
	s_barrier
	s_add_i32 s44, s58, s21
	v_lshl_add_u64 v[216:217], v[216:217], 0, s[14:15]
	s_mov_b32 m0, s44
	ds_read_b128 v[172:175], v185 offset:49152
	ds_read_b128 v[188:191], v185 offset:50176
	ds_read_b128 v[192:195], v185 offset:51200
	ds_read_b128 v[196:199], v185 offset:52224
	ds_read_b128 v[200:203], v185 offset:53248
	ds_read_b128 v[204:207], v185 offset:54272
	ds_read_b128 v[208:211], v185 offset:55296
	ds_read_b128 v[212:215], v185 offset:56320
	global_load_lds_dwordx4 v[216:217], off
	s_add_i32 m0, s44, 0x2000
	s_add_u32 s42, s42, 0x80080
	v_lshl_add_u64 v[216:217], v[218:219], 0, s[14:15]
	s_addc_u32 s43, s43, 0
	s_add_i32 s44, s59, s21
	global_load_lds_dwordx4 v[216:217], off
	s_mov_b32 m0, s44
	s_nop 0
	global_load_lds_dwordx4 v150, s[42:43]
	s_add_i32 m0, s44, 0x2000
	s_nop 0
	global_load_lds_dwordx4 v154, s[42:43]
	v_lshl_add_u64 v[216:217], v[220:221], 0, s[14:15]
	s_mov_b32 m0, s49
	s_nop 0
	global_load_lds_dwordx4 v[216:217], off
	v_lshl_add_u64 v[216:217], v[222:223], 0, s[14:15]
	s_mov_b32 m0, s50
	s_nop 0
	global_load_lds_dwordx4 v[216:217], off
	s_waitcnt vmcnt(8) lgkmcnt(0)
	s_barrier
	v_mfma_f32_16x16x32_bf16 v[60:63], v[64:67], v[172:175], v[60:63]
	v_mfma_f32_16x16x32_bf16 v[56:59], v[72:75], v[172:175], v[56:59]
	v_mfma_f32_16x16x32_bf16 v[44:47], v[64:67], v[192:195], v[44:47]
	v_mfma_f32_16x16x32_bf16 v[40:43], v[72:75], v[192:195], v[40:43]
	v_mfma_f32_16x16x32_bf16 v[24:27], v[64:67], v[200:203], v[24:27]
	v_mfma_f32_16x16x32_bf16 v[20:23], v[72:75], v[200:203], v[20:23]
	v_mfma_f32_16x16x32_bf16 v[8:11], v[64:67], v[208:211], v[8:11]
	v_mfma_f32_16x16x32_bf16 v[0:3], v[72:75], v[208:211], v[0:3]
	v_mfma_f32_16x16x32_bf16 v[60:63], v[68:71], v[188:191], v[60:63]
	v_mfma_f32_16x16x32_bf16 v[56:59], v[76:79], v[188:191], v[56:59]
	v_mfma_f32_16x16x32_bf16 v[44:47], v[68:71], v[196:199], v[44:47]
	v_mfma_f32_16x16x32_bf16 v[40:43], v[76:79], v[196:199], v[40:43]
	v_mfma_f32_16x16x32_bf16 v[24:27], v[68:71], v[204:207], v[24:27]
	v_mfma_f32_16x16x32_bf16 v[20:23], v[76:79], v[204:207], v[20:23]
	v_mfma_f32_16x16x32_bf16 v[8:11], v[68:71], v[212:215], v[8:11]
	v_mfma_f32_16x16x32_bf16 v[0:3], v[76:79], v[212:215], v[0:3]
	v_mfma_f32_16x16x32_bf16 v[52:55], v[144:147], v[172:175], v[52:55]
	v_mfma_f32_16x16x32_bf16 v[48:51], v[164:167], v[172:175], v[48:51]
	v_mfma_f32_16x16x32_bf16 v[36:39], v[144:147], v[192:195], v[36:39]
	v_mfma_f32_16x16x32_bf16 v[32:35], v[164:167], v[192:195], v[32:35]
	v_mfma_f32_16x16x32_bf16 v[28:31], v[144:147], v[200:203], v[28:31]
	v_mfma_f32_16x16x32_bf16 v[16:19], v[164:167], v[200:203], v[16:19]
	v_mfma_f32_16x16x32_bf16 v[12:15], v[144:147], v[208:211], v[12:15]
	v_mfma_f32_16x16x32_bf16 v[4:7], v[164:167], v[208:211], v[4:7]
	v_mfma_f32_16x16x32_bf16 v[52:55], v[160:163], v[188:191], v[52:55]
	v_mfma_f32_16x16x32_bf16 v[48:51], v[168:171], v[188:191], v[48:51]
	v_mfma_f32_16x16x32_bf16 v[36:39], v[160:163], v[196:199], v[36:39]
	v_mfma_f32_16x16x32_bf16 v[32:35], v[168:171], v[196:199], v[32:35]
	v_mfma_f32_16x16x32_bf16 v[28:31], v[160:163], v[204:207], v[28:31]
	v_mfma_f32_16x16x32_bf16 v[16:19], v[168:171], v[204:207], v[16:19]
	v_mfma_f32_16x16x32_bf16 v[12:15], v[160:163], v[212:215], v[12:15]
	v_mfma_f32_16x16x32_bf16 v[4:7], v[168:171], v[212:215], v[4:7]
	s_barrier
	s_add_i32 s57, s57, 2
	s_add_u32 s36, s36, 0x100
	s_addc_u32 s37, s37, 0
	s_add_u32 s25, s25, 0x100
	s_addc_u32 s56, s56, 0
	s_cmp_gt_u32 s57, 29
	s_cbranch_scc0 .LBB0_1037
	s_setprio 0
	s_and_b64 vcc, exec, s[16:17]
	s_mov_b32 s56, s62
	s_cbranch_vccz .LBB0_1040
	s_barrier

; #define PG8_STAGE(bufoff, gbase, voff) do { _Pragma("unroll") for (int _i = 0; _i < 2; ++_i) \
;         __builtin_amdgcn_global_load_lds((const unsigned*)((const char*)(gbase) + (voff)[_i]), (LAS unsigned*)(lds + (bufoff) + ldsw + _i * 8192), 16, 0, 0); } while (0)
; #define PG8_LDA(dst, b, h) do { _Pragma("unroll") for (int m = 0; m < 4; ++m) _Pragma("unroll") for (int k = 0; k < 2; ++k) dst[m][k] = *(const LAS bf16x8*)(lds + PG8_SA(b, h) + aoff + m * 2048 + k * 1024); } while (0)
; #define PG8_LDB(dst, b, h) do { _Pragma("unroll") for (int n = 0; n < 2; ++n) _Pragma("unroll") for (int k = 0; k < 2; ++k) dst[n][k] = *(const LAS bf16x8*)(lds + PG8_SB(b, h) + boff + n * 2048 + k * 1024); } while (0)
; #define PG8_MMA(ai, bj, At, Bt) do { __builtin_amdgcn_s_setprio(1); _Pragma("unroll") for (int m = 0; m < 4; ++m) _Pragma("unroll") for (int n = 0; n < 2; ++n) _Pragma("unroll") for (int k = 0; k < 2; ++k) \
;         acc[ai][bj][m][n] = __builtin_amdgcn_mfma_f32_16x16x32_bf16(Bt[n][k], At[m][k], acc[ai][bj][m][n], 0, 0, 0); __builtin_amdgcn_s_setprio(0); } while (0)
; #define PG8_WAIT_V(n) asm volatile("s_waitcnt vmcnt(" #n ")" ::: "memory")
; #define PG8_WAIT_L(n) asm volatile("s_waitcnt lgkmcnt(" #n ")" ::: "memory")
; #define PG8_BAR __builtin_amdgcn_s_barrier()
; #define PG8_SCHED __builtin_amdgcn_sched_barrier(0)
; template <class Sched, class Epi, bool ALIGN_EPI, bool SP2>
; __device__ __forceinline__ void gemm_phase(LAS unsigned char* lds, const int K, const int lda, const int ldb, const Sched& S, const Epi& E) {
;     ...
;             PG8_LDB(B0, 0, 0); PG8_LDB(B1, 0, 1); PG8_SCHED; PG8_LDA(At, 0, 0); PG8_STAGE(PG8_SA(1, 1), a1 + hstepA, voffA);
;             PG8_WAIT_V(8); PG8_WAIT_L(0); PG8_BAR; PG8_MMA(0, 0, At, B0); PG8_MMA(0, 1, At, B1); PG8_BAR; PG8_SCHED;
;             PG8_LDA(At, 0, 1); PG8_STAGE(PG8_SB(0, 0), b2, voffB); PG8_STAGE(PG8_SB(0, 1), b2 + hstepB, voffB); PG8_STAGE(PG8_SA(0, 0), a2, voffA);
;             PG8_WAIT_V(8); PG8_WAIT_L(0); PG8_BAR; PG8_MMA(1, 0, At, B0); PG8_MMA(1, 1, At, B1); PG8_BAR; PG8_SCHED;
.Lprio_skip_1120:
.LBB0_1120:
	ds_read_b128 v[96:99], v178
	ds_read_b128 v[100:103], v178 offset:1024
	ds_read_b128 v[104:107], v178 offset:2048
	ds_read_b128 v[108:111], v178 offset:3072
	ds_read_b128 v[112:115], v180
	ds_read_b128 v[116:119], v180 offset:1024
	ds_read_b128 v[120:123], v180 offset:2048
	ds_read_b128 v[124:127], v180 offset:3072
	s_add_u32 s4, s0, 0x100
	s_addc_u32 s5, s1, 0
	s_cmpk_eq_i32 s51, 0x54
	s_cselect_b32 s27, s21, s5
	s_cselect_b32 s26, s20, s4
	s_cselect_b32 s25, s23, s50
	s_cselect_b32 s24, s22, s49
	s_add_i32 m0, s17, 0xc000
	ds_read_b128 v[168:171], v181
	ds_read_b128 v[184:187], v181 offset:1024
	ds_read_b128 v[188:191], v181 offset:2048
	ds_read_b128 v[192:195], v181 offset:3072
	ds_read_b128 v[196:199], v181 offset:4096
	ds_read_b128 v[200:203], v181 offset:5120
	ds_read_b128 v[204:207], v181 offset:6144
	ds_read_b128 v[208:211], v181 offset:7168
	global_load_lds_dwordx4 v164, s[0:1]
	s_add_i32 m0, s17, 0xe000
	s_nop 0
	global_load_lds_dwordx4 v166, s[0:1]
	s_waitcnt vmcnt(8) lgkmcnt(0)
	s_barrier
	v_mfma_f32_16x16x32_bf16 v[156:159], v[96:99], v[168:171], v[156:159]
	v_mfma_f32_16x16x32_bf16 v[152:155], v[104:107], v[168:171], v[152:155]
	v_mfma_f32_16x16x32_bf16 v[144:147], v[96:99], v[188:191], v[144:147]
	v_mfma_f32_16x16x32_bf16 v[136:139], v[104:107], v[188:191], v[136:139]
	v_mfma_f32_16x16x32_bf16 v[92:95], v[96:99], v[196:199], v[92:95]
	v_mfma_f32_16x16x32_bf16 v[88:91], v[104:107], v[196:199], v[88:91]
	v_mfma_f32_16x16x32_bf16 v[80:83], v[96:99], v[204:207], v[80:83]
	v_mfma_f32_16x16x32_bf16 v[72:75], v[104:107], v[204:207], v[72:75]
	v_mfma_f32_16x16x32_bf16 v[156:159], v[100:103], v[184:187], v[156:159]
	v_mfma_f32_16x16x32_bf16 v[152:155], v[108:111], v[184:187], v[152:155]
	v_mfma_f32_16x16x32_bf16 v[144:147], v[100:103], v[192:195], v[144:147]
	v_mfma_f32_16x16x32_bf16 v[136:139], v[108:111], v[192:195], v[136:139]
	v_mfma_f32_16x16x32_bf16 v[92:95], v[100:103], v[200:203], v[92:95]
	v_mfma_f32_16x16x32_bf16 v[88:91], v[108:111], v[200:203], v[88:91]
	v_mfma_f32_16x16x32_bf16 v[80:83], v[100:103], v[208:211], v[80:83]
	v_mfma_f32_16x16x32_bf16 v[72:75], v[108:111], v[208:211], v[72:75]
	v_mfma_f32_16x16x32_bf16 v[148:151], v[112:115], v[168:171], v[148:151]
	v_mfma_f32_16x16x32_bf16 v[140:143], v[120:123], v[168:171], v[140:143]
	v_mfma_f32_16x16x32_bf16 v[132:135], v[112:115], v[188:191], v[132:135]
	v_mfma_f32_16x16x32_bf16 v[128:131], v[120:123], v[188:191], v[128:131]
	v_mfma_f32_16x16x32_bf16 v[84:87], v[112:115], v[196:199], v[84:87]
	v_mfma_f32_16x16x32_bf16 v[76:79], v[120:123], v[196:199], v[76:79]
	v_mfma_f32_16x16x32_bf16 v[68:71], v[112:115], v[204:207], v[68:71]
	v_mfma_f32_16x16x32_bf16 v[64:67], v[120:123], v[204:207], v[64:67]
	v_mfma_f32_16x16x32_bf16 v[148:151], v[116:119], v[184:187], v[148:151]
	v_mfma_f32_16x16x32_bf16 v[140:143], v[124:127], v[184:187], v[140:143]
	v_mfma_f32_16x16x32_bf16 v[132:135], v[116:119], v[192:195], v[132:135]
	v_mfma_f32_16x16x32_bf16 v[128:131], v[124:127], v[192:195], v[128:131]
	v_mfma_f32_16x16x32_bf16 v[84:87], v[116:119], v[200:203], v[84:87]
	v_mfma_f32_16x16x32_bf16 v[76:79], v[124:127], v[200:203], v[76:79]
	v_mfma_f32_16x16x32_bf16 v[68:71], v[116:119], v[208:211], v[68:71]
	v_mfma_f32_16x16x32_bf16 v[64:67], v[124:127], v[208:211], v[64:67]
	s_barrier
	s_add_i32 s0, s42, s15
	v_lshl_add_u64 v[172:173], s[24:25], 0, v[160:161]
	s_mov_b32 m0, s0
	ds_read_b128 v[168:171], v181 offset:16384
	ds_read_b128 v[184:187], v181 offset:17408
	ds_read_b128 v[188:191], v181 offset:18432
	ds_read_b128 v[192:195], v181 offset:19456
	ds_read_b128 v[196:199], v181 offset:20480
	ds_read_b128 v[200:203], v181 offset:21504
	ds_read_b128 v[204:207], v181 offset:22528
	ds_read_b128 v[208:211], v181 offset:23552
	global_load_lds_dwordx4 v[172:173], off
	s_add_i32 m0, s0, 0x2000
	s_add_u32 s0, s24, 0x160000
	v_lshl_add_u64 v[212:213], s[24:25], 0, v[162:163]
	s_addc_u32 s1, s25, 0
	s_add_i32 s52, s43, s15
	global_load_lds_dwordx4 v[212:213], off
	s_mov_b32 m0, s52
	v_lshl_add_u64 v[216:217], s[26:27], 0, v[162:163]
	global_load_lds_dwordx4 v160, s[0:1]
	s_add_i32 m0, s52, 0x2000
	s_nop 0
	global_load_lds_dwordx4 v162, s[0:1]
	v_lshl_add_u64 v[214:215], s[26:27], 0, v[160:161]
	s_mov_b32 m0, s17
	s_nop 0
	global_load_lds_dwordx4 v[214:215], off
	s_mov_b32 m0, s28
	s_nop 0
	global_load_lds_dwordx4 v[216:217], off
	s_waitcnt vmcnt(8) lgkmcnt(0)
	s_barrier
	v_mfma_f32_16x16x32_bf16 v[60:63], v[96:99], v[168:171], v[60:63]
	v_mfma_f32_16x16x32_bf16 v[56:59], v[104:107], v[168:171], v[56:59]
	v_mfma_f32_16x16x32_bf16 v[48:51], v[96:99], v[188:191], v[48:51]
	v_mfma_f32_16x16x32_bf16 v[40:43], v[104:107], v[188:191], v[40:43]
	v_mfma_f32_16x16x32_bf16 v[28:31], v[96:99], v[196:199], v[28:31]
	v_mfma_f32_16x16x32_bf16 v[24:27], v[104:107], v[196:199], v[24:27]
	v_mfma_f32_16x16x32_bf16 v[16:19], v[96:99], v[204:207], v[16:19]
	v_mfma_f32_16x16x32_bf16 v[8:11], v[104:107], v[204:207], v[8:11]
	v_mfma_f32_16x16x32_bf16 v[60:63], v[100:103], v[184:187], v[60:63]
	v_mfma_f32_16x16x32_bf16 v[56:59], v[108:111], v[184:187], v[56:59]
	v_mfma_f32_16x16x32_bf16 v[48:51], v[100:103], v[192:195], v[48:51]
	v_mfma_f32_16x16x32_bf16 v[40:43], v[108:111], v[192:195], v[40:43]
	v_mfma_f32_16x16x32_bf16 v[28:31], v[100:103], v[200:203], v[28:31]
	v_mfma_f32_16x16x32_bf16 v[24:27], v[108:111], v[200:203], v[24:27]
	v_mfma_f32_16x16x32_bf16 v[16:19], v[100:103], v[208:211], v[16:19]
	v_mfma_f32_16x16x32_bf16 v[8:11], v[108:111], v[208:211], v[8:11]
	v_mfma_f32_16x16x32_bf16 v[52:55], v[112:115], v[168:171], v[52:55]
	v_mfma_f32_16x16x32_bf16 v[44:47], v[120:123], v[168:171], v[44:47]
	v_mfma_f32_16x16x32_bf16 v[36:39], v[112:115], v[188:191], v[36:39]
	v_mfma_f32_16x16x32_bf16 v[32:35], v[120:123], v[188:191], v[32:35]
	v_mfma_f32_16x16x32_bf16 v[20:23], v[112:115], v[196:199], v[20:23]
	v_mfma_f32_16x16x32_bf16 v[12:15], v[120:123], v[196:199], v[12:15]
	v_mfma_f32_16x16x32_bf16 v[4:7], v[112:115], v[204:207], v[4:7]
	v_mfma_f32_16x16x32_bf16 v[0:3], v[120:123], v[204:207], v[0:3]
	v_mfma_f32_16x16x32_bf16 v[52:55], v[116:119], v[184:187], v[52:55]
	v_mfma_f32_16x16x32_bf16 v[44:47], v[124:127], v[184:187], v[44:47]
	v_mfma_f32_16x16x32_bf16 v[36:39], v[116:119], v[192:195], v[36:39]
	v_mfma_f32_16x16x32_bf16 v[32:35], v[124:127], v[192:195], v[32:35]
	v_mfma_f32_16x16x32_bf16 v[20:23], v[116:119], v[200:203], v[20:23]
	v_mfma_f32_16x16x32_bf16 v[12:15], v[124:127], v[200:203], v[12:15]
	v_mfma_f32_16x16x32_bf16 v[4:7], v[116:119], v[208:211], v[4:7]
	v_mfma_f32_16x16x32_bf16 v[0:3], v[124:127], v[208:211], v[0:3]
	s_barrier
; #define PG8_STAGE(bufoff, gbase, voff) do { _Pragma("unroll") for (int _i = 0; _i < 2; ++_i) \
;         __builtin_amdgcn_global_load_lds((const unsigned*)((const char*)(gbase) + (voff)[_i]), (LAS unsigned*)(lds + (bufoff) + ldsw + _i * 8192), 16, 0, 0); } while (0)
; #define PG8_LDA(dst, b, h) do { _Pragma("unroll") for (int m = 0; m < 4; ++m) _Pragma("unroll") for (int k = 0; k < 2; ++k) dst[m][k] = *(const LAS bf16x8*)(lds + PG8_SA(b, h) + aoff + m * 2048 + k * 1024); } while (0)
; #define PG8_LDB(dst, b, h) do { _Pragma("unroll") for (int n = 0; n < 2; ++n) _Pragma("unroll") for (int k = 0; k < 2; ++k) dst[n][k] = *(const LAS bf16x8*)(lds + PG8_SB(b, h) + boff + n * 2048 + k * 1024); } while (0)
; #define PG8_MMA(ai, bj, At, Bt) do { __builtin_amdgcn_s_setprio(1); _Pragma("unroll") for (int m = 0; m < 4; ++m) _Pragma("unroll") for (int n = 0; n < 2; ++n) _Pragma("unroll") for (int k = 0; k < 2; ++k) \
;         acc[ai][bj][m][n] = __builtin_amdgcn_mfma_f32_16x16x32_bf16(Bt[n][k], At[m][k], acc[ai][bj][m][n], 0, 0, 0); __builtin_amdgcn_s_setprio(0); } while (0)
; #define PG8_WAIT_V(n) asm volatile("s_waitcnt vmcnt(" #n ")" ::: "memory")
; #define PG8_WAIT_L(n) asm volatile("s_waitcnt lgkmcnt(" #n ")" ::: "memory")
; #define PG8_BAR __builtin_amdgcn_s_barrier()
; #define PG8_SCHED __builtin_amdgcn_sched_barrier(0)
; template <class Sched, class Epi, bool ALIGN_EPI, bool SP2>
; __device__ __forceinline__ void gemm_phase(LAS unsigned char* lds, const int K, const int lda, const int ldb, const Sched& S, const Epi& E) {
;     ...
;             PG8_LDB(B0, 1, 0); PG8_LDB(B1, 1, 1); PG8_SCHED; PG8_LDA(At, 1, 0); PG8_STAGE(PG8_SA(0, 1), a2 + hstepA, voffA);
;             PG8_WAIT_V(8); PG8_WAIT_L(0); PG8_BAR; PG8_MMA(0, 0, At, B0); PG8_MMA(0, 1, At, B1); PG8_BAR; PG8_SCHED;
;             PG8_LDA(At, 1, 1); PG8_STAGE(PG8_SB(1, 0), b3, voffB); PG8_STAGE(PG8_SB(1, 1), b3 + hstepB, voffB); PG8_STAGE(PG8_SA(1, 0), a3, voffA);
;             PG8_WAIT_V(8); PG8_WAIT_L(0); PG8_BAR; PG8_MMA(1, 0, At, B0); PG8_MMA(1, 1, At, B1); PG8_BAR; PG8_SCHED;
	s_add_i32 s52, 0, 0x18000
	s_add_i32 s53, 0, 0x1c000
	v_add_u32_e32 v108, s52, v175
	v_add_u32_e32 v124, s53, v175
	ds_read_b128 v[96:99], v108
	ds_read_b128 v[100:103], v108 offset:1024
	ds_read_b128 v[104:107], v108 offset:2048
	ds_read_b128 v[108:111], v108 offset:3072
	ds_read_b128 v[112:115], v124
	ds_read_b128 v[116:119], v124 offset:1024
	ds_read_b128 v[120:123], v124 offset:2048
	ds_read_b128 v[124:127], v124 offset:3072
	s_add_u32 s0, s26, 0x160000
	s_addc_u32 s1, s27, 0
	s_mov_b32 m0, s29
	ds_read_b128 v[168:171], v181 offset:32768
	ds_read_b128 v[184:187], v181 offset:33792
	ds_read_b128 v[188:191], v181 offset:34816
	ds_read_b128 v[192:195], v181 offset:35840
	ds_read_b128 v[196:199], v181 offset:36864
	ds_read_b128 v[200:203], v181 offset:37888
	ds_read_b128 v[204:207], v181 offset:38912
	ds_read_b128 v[208:211], v181 offset:39936
	global_load_lds_dwordx4 v160, s[0:1]
	s_mov_b32 m0, s33
	s_nop 0
	global_load_lds_dwordx4 v162, s[0:1]
	s_waitcnt vmcnt(8) lgkmcnt(0)
	s_barrier
	v_mfma_f32_16x16x32_bf16 v[156:159], v[96:99], v[168:171], v[156:159]
	v_mfma_f32_16x16x32_bf16 v[152:155], v[104:107], v[168:171], v[152:155]
	v_mfma_f32_16x16x32_bf16 v[144:147], v[96:99], v[188:191], v[144:147]
	v_mfma_f32_16x16x32_bf16 v[136:139], v[104:107], v[188:191], v[136:139]
	v_mfma_f32_16x16x32_bf16 v[92:95], v[96:99], v[196:199], v[92:95]
	v_mfma_f32_16x16x32_bf16 v[88:91], v[104:107], v[196:199], v[88:91]
	v_mfma_f32_16x16x32_bf16 v[80:83], v[96:99], v[204:207], v[80:83]
	v_mfma_f32_16x16x32_bf16 v[72:75], v[104:107], v[204:207], v[72:75]
	v_mfma_f32_16x16x32_bf16 v[156:159], v[100:103], v[184:187], v[156:159]
	v_mfma_f32_16x16x32_bf16 v[152:155], v[108:111], v[184:187], v[152:155]
	v_mfma_f32_16x16x32_bf16 v[144:147], v[100:103], v[192:195], v[144:147]
	v_mfma_f32_16x16x32_bf16 v[136:139], v[108:111], v[192:195], v[136:139]
	v_mfma_f32_16x16x32_bf16 v[92:95], v[100:103], v[200:203], v[92:95]
	v_mfma_f32_16x16x32_bf16 v[88:91], v[108:111], v[200:203], v[88:91]
	v_mfma_f32_16x16x32_bf16 v[80:83], v[100:103], v[208:211], v[80:83]
	v_mfma_f32_16x16x32_bf16 v[72:75], v[108:111], v[208:211], v[72:75]
	v_mfma_f32_16x16x32_bf16 v[148:151], v[112:115], v[168:171], v[148:151]
	v_mfma_f32_16x16x32_bf16 v[140:143], v[120:123], v[168:171], v[140:143]
	v_mfma_f32_16x16x32_bf16 v[132:135], v[112:115], v[188:191], v[132:135]
	v_mfma_f32_16x16x32_bf16 v[128:131], v[120:123], v[188:191], v[128:131]
	v_mfma_f32_16x16x32_bf16 v[84:87], v[112:115], v[196:199], v[84:87]
	v_mfma_f32_16x16x32_bf16 v[76:79], v[120:123], v[196:199], v[76:79]
	v_mfma_f32_16x16x32_bf16 v[68:71], v[112:115], v[204:207], v[68:71]
	v_mfma_f32_16x16x32_bf16 v[64:67], v[120:123], v[204:207], v[64:67]
	v_mfma_f32_16x16x32_bf16 v[148:151], v[116:119], v[184:187], v[148:151]
	v_mfma_f32_16x16x32_bf16 v[140:143], v[124:127], v[184:187], v[140:143]
	v_mfma_f32_16x16x32_bf16 v[132:135], v[116:119], v[192:195], v[132:135]
	v_mfma_f32_16x16x32_bf16 v[128:131], v[124:127], v[192:195], v[128:131]
	v_mfma_f32_16x16x32_bf16 v[84:87], v[116:119], v[200:203], v[84:87]
	v_mfma_f32_16x16x32_bf16 v[76:79], v[124:127], v[200:203], v[76:79]
	v_mfma_f32_16x16x32_bf16 v[68:71], v[116:119], v[208:211], v[68:71]
	v_mfma_f32_16x16x32_bf16 v[64:67], v[124:127], v[208:211], v[64:67]
	s_barrier
	s_add_i32 s0, s52, s15
	v_lshl_add_u64 v[172:173], v[172:173], 0, s[10:11]
	s_mov_b32 m0, s0
	ds_read_b128 v[168:171], v181 offset:49152
	ds_read_b128 v[184:187], v181 offset:50176
	ds_read_b128 v[188:191], v181 offset:51200
	ds_read_b128 v[192:195], v181 offset:52224
	ds_read_b128 v[196:199], v181 offset:53248
	ds_read_b128 v[200:203], v181 offset:54272
	ds_read_b128 v[204:207], v181 offset:55296
	ds_read_b128 v[208:211], v181 offset:56320
	global_load_lds_dwordx4 v[172:173], off
	s_add_i32 m0, s0, 0x2000
	s_add_u32 s0, s24, 0x160080
	v_lshl_add_u64 v[172:173], v[212:213], 0, s[10:11]
	s_addc_u32 s1, s25, 0
	s_add_i32 s24, s53, s15
	global_load_lds_dwordx4 v[172:173], off
	s_mov_b32 m0, s24
	s_nop 0
	global_load_lds_dwordx4 v160, s[0:1]
	s_add_i32 m0, s24, 0x2000
	s_nop 0
	global_load_lds_dwordx4 v162, s[0:1]
	v_lshl_add_u64 v[172:173], v[214:215], 0, s[10:11]
	s_mov_b32 m0, s36
	s_nop 0
	global_load_lds_dwordx4 v[172:173], off
	v_lshl_add_u64 v[172:173], v[216:217], 0, s[10:11]
	s_mov_b32 m0, s37
	s_nop 0
	global_load_lds_dwordx4 v[172:173], off
	s_waitcnt vmcnt(8) lgkmcnt(0)
	s_barrier
	v_mfma_f32_16x16x32_bf16 v[60:63], v[96:99], v[168:171], v[60:63]
	v_mfma_f32_16x16x32_bf16 v[56:59], v[104:107], v[168:171], v[56:59]
	v_mfma_f32_16x16x32_bf16 v[48:51], v[96:99], v[188:191], v[48:51]
	v_mfma_f32_16x16x32_bf16 v[40:43], v[104:107], v[188:191], v[40:43]
	v_mfma_f32_16x16x32_bf16 v[28:31], v[96:99], v[196:199], v[28:31]
	v_mfma_f32_16x16x32_bf16 v[24:27], v[104:107], v[196:199], v[24:27]
	v_mfma_f32_16x16x32_bf16 v[16:19], v[96:99], v[204:207], v[16:19]
	v_mfma_f32_16x16x32_bf16 v[8:11], v[104:107], v[204:207], v[8:11]
	v_mfma_f32_16x16x32_bf16 v[60:63], v[100:103], v[184:187], v[60:63]
	v_mfma_f32_16x16x32_bf16 v[56:59], v[108:111], v[184:187], v[56:59]
	v_mfma_f32_16x16x32_bf16 v[48:51], v[100:103], v[192:195], v[48:51]
	v_mfma_f32_16x16x32_bf16 v[40:43], v[108:111], v[192:195], v[40:43]
	v_mfma_f32_16x16x32_bf16 v[28:31], v[100:103], v[200:203], v[28:31]
	v_mfma_f32_16x16x32_bf16 v[24:27], v[108:111], v[200:203], v[24:27]
	v_mfma_f32_16x16x32_bf16 v[16:19], v[100:103], v[208:211], v[16:19]
	v_mfma_f32_16x16x32_bf16 v[8:11], v[108:111], v[208:211], v[8:11]
	v_mfma_f32_16x16x32_bf16 v[52:55], v[112:115], v[168:171], v[52:55]
	v_mfma_f32_16x16x32_bf16 v[44:47], v[120:123], v[168:171], v[44:47]
	v_mfma_f32_16x16x32_bf16 v[36:39], v[112:115], v[188:191], v[36:39]
	v_mfma_f32_16x16x32_bf16 v[32:35], v[120:123], v[188:191], v[32:35]
	v_mfma_f32_16x16x32_bf16 v[20:23], v[112:115], v[196:199], v[20:23]
	v_mfma_f32_16x16x32_bf16 v[12:15], v[120:123], v[196:199], v[12:15]
	v_mfma_f32_16x16x32_bf16 v[4:7], v[112:115], v[204:207], v[4:7]
	v_mfma_f32_16x16x32_bf16 v[0:3], v[120:123], v[204:207], v[0:3]
	v_mfma_f32_16x16x32_bf16 v[52:55], v[116:119], v[184:187], v[52:55]
	v_mfma_f32_16x16x32_bf16 v[44:47], v[124:127], v[184:187], v[44:47]
	v_mfma_f32_16x16x32_bf16 v[36:39], v[116:119], v[192:195], v[36:39]
	v_mfma_f32_16x16x32_bf16 v[32:35], v[124:127], v[192:195], v[32:35]
	v_mfma_f32_16x16x32_bf16 v[20:23], v[116:119], v[200:203], v[20:23]
	v_mfma_f32_16x16x32_bf16 v[12:15], v[124:127], v[200:203], v[12:15]
	v_mfma_f32_16x16x32_bf16 v[4:7], v[116:119], v[208:211], v[4:7]
	v_mfma_f32_16x16x32_bf16 v[0:3], v[124:127], v[208:211], v[0:3]
	s_barrier
	s_add_i32 s51, s51, 2
	s_add_u32 s49, s49, 0x100
	s_addc_u32 s50, s50, 0
	s_cmpk_gt_u32 s51, 0x55
	s_mov_b64 s[0:1], s[4:5]
	s_cbranch_scc0 .LBB0_1120
	s_setprio 0
	s_and_b64 vcc, exec, s[12:13]
	s_cbranch_vccz .LBB0_1123
	s_barrier
